# on top of the previous version: 64-bit register moves for the softmax accumulator init in the three attention loops, and the no-op canonicalising v_max removed from the squared-ReLU GEMM epilogue; no
# speedup vs baseline: 1.0281x; 1.0037x over previous
; DI f32x16 mfma32(bf16x8 a, bf16x8 b, f32x16 c) { return __builtin_amdgcn_mfma_f32_32x32x16_bf16(a, b, c, 0, 0, 0); }
; DI void attn_diff_unit(const Params& p, int li, int b, int h, int qb, char* smem, bool pre, int nh, bool has_next) {
;     ...
;       f32x16 s0, s1;
; #pragma unroll
;       for (int i = 0; i < 16; ++i) { s0[i] = cb - m; s1[i] = cb - m; }
;       {
;         bf16x8 kf[8];
; #pragma unroll
;         for (int s = 0; s < 4; ++s) {
;           kf[2 * s] = *(const bf16x8*)(ks + (sub * 64 + r32) * KR + (map * 64 + s * 16 + hh * 8) * 2);
;           kf[2 * s + 1] = *(const bf16x8*)(ks + (sub * 64 + 32 + r32) * KR + (map * 64 + s * 16 + hh * 8) * 2);
;         }
;         __builtin_amdgcn_sched_barrier(0); __builtin_amdgcn_s_setprio(1);
; #pragma unroll
;         for (int s = 0; s < 4; ++s) { s0 = mfma32(kf[2 * s], qf[s], s0); s1 = mfma32(kf[2 * s + 1], qf[s], s1); }
;       __builtin_amdgcn_s_setprio(0);
; }
;       if (relmin < 128 && relmax > -128) {
;         const int base = kbase - qpos + 255 + 4 * hh;
; #pragma unroll
;         for (int i = 0; i < 16; ++i) {
;           int i0 = base + (i & 3) + 8 * (i >> 2);
;           int i1 = i0 + 32;
;           i0 = i0 < 0 ? 0 : (i0 > 510 ? 510 : i0);
;           i1 = i1 < 0 ? 0 : (i1 > 510 ? 510 : i1);
;           s0[i] += tab[i0]; s1[i] += tab[i1];
;         }
;       }
.LBB0_568:
	v_add_u32_e32 v76, s45, v167
	v_add_u32_e32 v174, v76, v165
	ds_read_b128 v[176:179], v174
	ds_read_b128 v[196:199], v174 offset:32
	ds_read_b128 v[200:203], v174 offset:8704
	ds_read_b128 v[204:207], v174 offset:8736
	ds_read_b128 v[208:211], v174 offset:64
	ds_read_b128 v[212:215], v174 offset:96
	ds_read_b128 v[216:219], v174 offset:8768
	ds_read_b128 v[220:223], v174 offset:8800
	s_add_i32 s44, s42, s24
	s_cmp_ge_i32 s44, 0xff
	s_cselect_b64 vcc, -1, 0
	s_cmp_le_i32 s44, 0xffffff41
	s_cselect_b64 s[2:3], -1, 0
	v_cndmask_b32_e64 v64, 0, v156, s[2:3]
	v_cndmask_b32_e32 v64, v64, v157, vcc
	v_sub_f32_e32 v64, v64, v169
	v_mov_b32_e32 v65, v64
	v_mov_b64_e32 v[66:67], v[64:65]
	v_mov_b64_e32 v[68:69], v[64:65]
	v_mov_b64_e32 v[70:71], v[64:65]
	v_mov_b64_e32 v[72:73], v[64:65]
	v_mov_b64_e32 v[74:75], v[64:65]
	v_mov_b64_e32 v[76:77], v[64:65]
	v_mov_b64_e32 v[78:79], v[64:65]
	s_nop 0
	s_waitcnt lgkmcnt(4)
	v_mfma_f32_32x32x16_bf16 v[80:95], v[176:179], v[96:99], v[64:79]
	v_mfma_f32_32x32x16_bf16 v[64:79], v[200:203], v[96:99], v[64:79]
	v_mfma_f32_32x32x16_bf16 v[80:95], v[196:199], v[100:103], v[80:95]
	v_mfma_f32_32x32x16_bf16 v[64:79], v[204:207], v[100:103], v[64:79]
	s_waitcnt lgkmcnt(0)
	v_mfma_f32_32x32x16_bf16 v[80:95], v[208:211], v[104:107], v[80:95]
	v_mfma_f32_32x32x16_bf16 v[64:79], v[216:219], v[104:107], v[64:79]
	v_mfma_f32_32x32x16_bf16 v[80:95], v[212:215], v[108:111], v[80:95]
	v_mfma_f32_32x32x16_bf16 v[64:79], v[220:223], v[108:111], v[64:79]
	s_or_b64 s[2:3], s[2:3], vcc
	v_add_u32_e32 v173, s24, v168
	s_and_b64 vcc, exec, s[2:3]
	s_cbranch_vccnz .LBB0_570
	v_add_u32_e32 v177, 0x100, v173
	s_add_i32 s2, 0, 0x25000
	v_med3_i32 v178, v177, 0, v192
	v_med3_i32 v177, v177, s33, v193
	v_lshl_add_u32 v180, v177, 2, s2
	v_add_u32_e32 v177, 0x101, v173
	v_lshl_add_u32 v179, v178, 2, s2
	v_med3_i32 v178, v177, 0, v192
	v_med3_i32 v177, v177, s33, v193
	v_add_u32_e32 v199, 0x108, v173
	v_add_u32_e32 v175, 0xff, v173
	v_lshl_add_u32 v196, v177, 2, s2
	v_add_u32_e32 v177, 0x102, v173
	v_med3_i32 v200, v199, 0, v192
	v_med3_i32 v199, v199, s33, v193
	v_med3_i32 v176, v175, 0, v192
	v_med3_i32 v175, v175, s33, v193
	v_lshl_add_u32 v181, v178, 2, s2
	v_med3_i32 v178, v177, 0, v192
	v_lshl_add_u32 v202, v199, 2, s2
	v_add_u32_e32 v199, 0x109, v173
	v_lshl_add_u32 v176, v176, 2, s2
	v_lshl_add_u32 v175, v175, 2, s2
	v_med3_i32 v177, v177, s33, v193
	v_lshl_add_u32 v197, v178, 2, s2
	v_lshl_add_u32 v201, v200, 2, s2
	v_med3_i32 v200, v199, 0, v192
	v_med3_i32 v199, v199, s33, v193
	v_add_u32_e32 v207, 0x110, v173
	v_lshl_add_u32 v198, v177, 2, s2
	ds_read_b32 v176, v176
	ds_read_b32 v178, v175 offset:128
	ds_read_b32 v177, v179
	ds_read_b32 v179, v180 offset:128
	ds_read_b32 v180, v181
	ds_read_b32 v196, v196 offset:128
	ds_read_b32 v181, v197
	ds_read_b32 v197, v198 offset:128
	v_add_u32_e32 v175, 0x107, v173
	v_lshl_add_u32 v204, v199, 2, s2
	v_add_u32_e32 v199, 0x10a, v173
	v_med3_i32 v208, v207, 0, v192
	v_med3_i32 v207, v207, s33, v193
	v_med3_i32 v198, v175, 0, v192
	v_med3_i32 v175, v175, s33, v193
	v_lshl_add_u32 v203, v200, 2, s2
	v_med3_i32 v200, v199, 0, v192
	v_lshl_add_u32 v210, v207, 2, s2
	v_add_u32_e32 v207, 0x111, v173
	v_lshl_add_u32 v198, v198, 2, s2
	v_lshl_add_u32 v175, v175, 2, s2
	v_med3_i32 v199, v199, s33, v193
	v_lshl_add_u32 v205, v200, 2, s2
	v_lshl_add_u32 v209, v208, 2, s2
	v_med3_i32 v208, v207, 0, v192
	v_med3_i32 v207, v207, s33, v193
	v_add_u32_e32 v215, 0x118, v173
	v_lshl_add_u32 v206, v199, 2, s2
	ds_read_b32 v198, v198
	ds_read_b32 v200, v175 offset:128
	ds_read_b32 v199, v201
	ds_read_b32 v201, v202 offset:128
	ds_read_b32 v202, v203
	ds_read_b32 v204, v204 offset:128
	ds_read_b32 v203, v205
	ds_read_b32 v205, v206 offset:128
	v_add_u32_e32 v175, 0x10f, v173
	v_lshl_add_u32 v212, v207, 2, s2
	v_add_u32_e32 v207, 0x112, v173
	v_med3_i32 v216, v215, 0, v192
	v_med3_i32 v215, v215, s33, v193
	v_med3_i32 v206, v175, 0, v192
	v_med3_i32 v175, v175, s33, v193
	v_lshl_add_u32 v211, v208, 2, s2
	v_med3_i32 v208, v207, 0, v192
	v_lshl_add_u32 v222, v215, 2, s2
	v_add_u32_e32 v215, 0x119, v173
	v_lshl_add_u32 v206, v206, 2, s2
	v_lshl_add_u32 v175, v175, 2, s2
	v_med3_i32 v207, v207, s33, v193
	v_lshl_add_u32 v213, v208, 2, s2
	v_lshl_add_u32 v217, v216, 2, s2
	v_med3_i32 v216, v215, 0, v192
	v_med3_i32 v215, v215, s33, v193
	v_lshl_add_u32 v214, v207, 2, s2
	ds_read_b32 v206, v206
	ds_read_b32 v208, v175 offset:128
	ds_read_b32 v207, v209
	ds_read_b32 v209, v210 offset:128
	ds_read_b32 v210, v211
	ds_read_b32 v212, v212 offset:128
	ds_read_b32 v211, v213
	ds_read_b32 v213, v214 offset:128
	v_add_u32_e32 v175, 0x117, v173
	v_lshl_add_u32 v220, v215, 2, s2
	v_add_u32_e32 v215, 0x11a, v173
	v_med3_i32 v214, v175, 0, v192
	v_lshl_add_u32 v218, v216, 2, s2
	v_med3_i32 v216, v215, 0, v192
	v_med3_i32 v215, v215, s33, v193
	v_med3_i32 v175, v175, s33, v193
	v_lshl_add_u32 v214, v214, 2, s2
	v_lshl_add_u32 v219, v216, 2, s2
	v_lshl_add_u32 v221, v215, 2, s2
	v_lshl_add_u32 v175, v175, 2, s2
	ds_read_b32 v214, v214
	ds_read_b32 v216, v175 offset:128
	ds_read_b32 v218, v218
	ds_read_b32 v219, v219
	ds_read_b32 v215, v217
	ds_read_b32 v221, v221 offset:128
	ds_read_b32 v220, v220 offset:128
	ds_read_b32 v217, v222 offset:128
	s_waitcnt lgkmcnt(4)
	v_pk_add_f32 v[94:95], v[94:95], v[218:219]
	s_waitcnt lgkmcnt(3)
	v_pk_add_f32 v[92:93], v[92:93], v[214:215]
	v_pk_add_f32 v[90:91], v[90:91], v[210:211]
	v_pk_add_f32 v[88:89], v[88:89], v[206:207]
	v_pk_add_f32 v[86:87], v[86:87], v[202:203]
	v_pk_add_f32 v[84:85], v[84:85], v[198:199]
	v_pk_add_f32 v[82:83], v[82:83], v[180:181]
	v_pk_add_f32 v[80:81], v[80:81], v[176:177]
	s_waitcnt lgkmcnt(1)
	v_pk_add_f32 v[78:79], v[78:79], v[220:221]
	s_waitcnt lgkmcnt(0)
	v_pk_add_f32 v[76:77], v[76:77], v[216:217]
	v_pk_add_f32 v[74:75], v[74:75], v[212:213]
	v_pk_add_f32 v[72:73], v[72:73], v[208:209]
	v_pk_add_f32 v[70:71], v[70:71], v[204:205]
	v_pk_add_f32 v[68:69], v[68:69], v[200:201]
	v_pk_add_f32 v[66:67], v[66:67], v[196:197]
	v_pk_add_f32 v[64:65], v[64:65], v[178:179]

; DI f32x16 mfma32(bf16x8 a, bf16x8 b, f32x16 c) { return __builtin_amdgcn_mfma_f32_32x32x16_bf16(a, b, c, 0, 0, 0); }
; DI void attn_diff_unit(const Params& p, int li, int b, int h, int qb, char* smem, bool pre, int nh, bool has_next) {
;     ...
;       const int kbase = kt * 128 + sub * 64;
;       const int relmin = kbase - (qb * 128 + 127), relmax = kbase + 63 - qb * 128;
;       const float cb = (relmin >= 128) ? cR : ((relmax <= -128) ? cL : 0.f);
;       f32x16 s0, s1;
; #pragma unroll
;       for (int i = 0; i < 16; ++i) { s0[i] = cb - m; s1[i] = cb - m; }
;       {
;         bf16x8 kf[8];
; #pragma unroll
;         for (int s = 0; s < 4; ++s) {
;           kf[2 * s] = *(const bf16x8*)(ks + (sub * 64 + r32) * KR + (map * 64 + s * 16 + hh * 8) * 2);
;           kf[2 * s + 1] = *(const bf16x8*)(ks + (sub * 64 + 32 + r32) * KR + (map * 64 + s * 16 + hh * 8) * 2);
;         }
;         __builtin_amdgcn_sched_barrier(0); __builtin_amdgcn_s_setprio(1);
; #pragma unroll
;         for (int s = 0; s < 4; ++s) { s0 = mfma32(kf[2 * s], qf[s], s0); s1 = mfma32(kf[2 * s + 1], qf[s], s1); }
;       __builtin_amdgcn_s_setprio(0);
; }
;       if (relmin < 128 && relmax > -128) {
;         const int base = kbase - qpos + 255 + 4 * hh;
; #pragma unroll
;         for (int i = 0; i < 16; ++i) {
;           int i0 = base + (i & 3) + 8 * (i >> 2);
;           int i1 = i0 + 32;
;           i0 = i0 < 0 ? 0 : (i0 > 510 ? 510 : i0);
;           i1 = i1 < 0 ? 0 : (i1 > 510 ? 510 : i1);
;           s0[i] += tab[i0]; s1[i] += tab[i1];
;         }
;       }
.Ldp_ck_done:
	v_cvt_pk_bf16_f32 v64, v64, v65
	v_cvt_pk_bf16_f32 v65, v66, v67
	v_cvt_pk_bf16_f32 v66, v68, v69
	v_cvt_pk_bf16_f32 v67, v70, v71
	v_cvt_pk_bf16_f32 v68, v72, v73
	v_cvt_pk_bf16_f32 v69, v74, v75
	v_cvt_pk_bf16_f32 v70, v76, v77
	v_cvt_pk_bf16_f32 v71, v78, v79
	v_cvt_pk_bf16_f32 v72, v80, v81
	v_cvt_pk_bf16_f32 v73, v82, v83
	v_cvt_pk_bf16_f32 v74, v84, v85
	v_cvt_pk_bf16_f32 v75, v86, v87
	v_cvt_pk_bf16_f32 v76, v88, v89
	v_cvt_pk_bf16_f32 v77, v90, v91
	v_cvt_pk_bf16_f32 v78, v92, v93
	v_cvt_pk_bf16_f32 v79, v94, v95
	s_add_i32 s2, s44, 64
	s_cmp_ge_i32 s2, 0xff
	s_cselect_b64 vcc, -1, 0
	s_cmp_le_i32 s2, 0xffffff41
	s_cselect_b64 s[2:3], -1, 0
	v_cndmask_b32_e64 v196, 0, v156, s[2:3]
	v_cndmask_b32_e32 v196, v196, v157, vcc
	v_sub_f32_e32 v196, v196, v169
	v_mov_b32_e32 v197, v196
	v_mov_b64_e32 v[198:199], v[196:197]
	v_mov_b64_e32 v[200:201], v[196:197]
	v_mov_b64_e32 v[202:203], v[196:197]
	v_mov_b64_e32 v[204:205], v[196:197]
	v_mov_b64_e32 v[206:207], v[196:197]
	v_mov_b64_e32 v[208:209], v[196:197]
	v_mov_b64_e32 v[210:211], v[196:197]
	s_waitcnt lgkmcnt(0)
	s_nop 0
	v_mfma_f32_32x32x16_bf16 v[80:95], v[212:215], v[96:99], v[196:211]
	v_mfma_f32_32x32x16_bf16 v[196:211], v[216:219], v[96:99], v[196:211]
	v_mfma_f32_32x32x16_bf16 v[80:95], v[220:223], v[100:103], v[80:95]
	v_mfma_f32_32x32x16_bf16 v[196:211], v[224:227], v[100:103], v[196:211]
	v_mfma_f32_32x32x16_bf16 v[80:95], v[228:231], v[104:107], v[80:95]
	v_mfma_f32_32x32x16_bf16 v[196:211], v[232:235], v[104:107], v[196:211]
	v_mfma_f32_32x32x16_bf16 v[80:95], v[176:179], v[108:111], v[80:95]
	v_mfma_f32_32x32x16_bf16 v[196:211], v[242:245], v[108:111], v[196:211]
	s_or_b64 s[2:3], s[2:3], vcc
	s_and_b64 vcc, exec, s[2:3]
	s_cbranch_vccnz .Ldp_b1_skip
	s_add_i32 s2, 0, 0x25000
	v_add_u32_e32 v212, 0x13f, v173
	v_add_u32_e32 v228, 0x13f, v173
	v_add_u32_e32 v213, 0x140, v173
	v_add_u32_e32 v229, 0x140, v173
	v_add_u32_e32 v214, 0x141, v173
	v_add_u32_e32 v230, 0x141, v173
	v_add_u32_e32 v215, 0x142, v173
	v_add_u32_e32 v231, 0x142, v173
	v_add_u32_e32 v216, 0x147, v173
	v_add_u32_e32 v232, 0x147, v173
	v_add_u32_e32 v217, 0x148, v173
	v_add_u32_e32 v233, 0x148, v173
	v_add_u32_e32 v218, 0x149, v173
	v_add_u32_e32 v234, 0x149, v173
	v_add_u32_e32 v219, 0x14a, v173
	v_add_u32_e32 v235, 0x14a, v173
	v_add_u32_e32 v220, 0x14f, v173
	v_add_u32_e32 v176, 0x14f, v173
	v_add_u32_e32 v221, 0x150, v173
	v_add_u32_e32 v177, 0x150, v173
	v_add_u32_e32 v222, 0x151, v173
	v_add_u32_e32 v178, 0x151, v173
	v_add_u32_e32 v223, 0x152, v173
	v_add_u32_e32 v179, 0x152, v173
	v_add_u32_e32 v224, 0x157, v173
	v_add_u32_e32 v242, 0x157, v173
	v_add_u32_e32 v225, 0x158, v173
	v_add_u32_e32 v243, 0x158, v173
	v_add_u32_e32 v226, 0x159, v173
	v_add_u32_e32 v244, 0x159, v173
	v_add_u32_e32 v227, 0x15a, v173
	v_add_u32_e32 v245, 0x15a, v173
	v_med3_i32 v212, v212, 0, v192
	v_med3_i32 v228, v228, s33, v193
	v_med3_i32 v213, v213, 0, v192
	v_med3_i32 v229, v229, s33, v193
	v_med3_i32 v214, v214, 0, v192
	v_med3_i32 v230, v230, s33, v193
	v_med3_i32 v215, v215, 0, v192
	v_med3_i32 v231, v231, s33, v193
	v_med3_i32 v216, v216, 0, v192
	v_med3_i32 v232, v232, s33, v193
	v_med3_i32 v217, v217, 0, v192
	v_med3_i32 v233, v233, s33, v193
	v_med3_i32 v218, v218, 0, v192
	v_med3_i32 v234, v234, s33, v193
	v_med3_i32 v219, v219, 0, v192
	v_med3_i32 v235, v235, s33, v193
	v_med3_i32 v220, v220, 0, v192
	v_med3_i32 v176, v176, s33, v193
	v_med3_i32 v221, v221, 0, v192
	v_med3_i32 v177, v177, s33, v193
	v_med3_i32 v222, v222, 0, v192
	v_med3_i32 v178, v178, s33, v193
	v_med3_i32 v223, v223, 0, v192
	v_med3_i32 v179, v179, s33, v193
	v_med3_i32 v224, v224, 0, v192
	v_med3_i32 v242, v242, s33, v193
	v_med3_i32 v225, v225, 0, v192
	v_med3_i32 v243, v243, s33, v193
	v_med3_i32 v226, v226, 0, v192
	v_med3_i32 v244, v244, s33, v193
	v_med3_i32 v227, v227, 0, v192
	v_med3_i32 v245, v245, s33, v193
	v_lshl_add_u32 v212, v212, 2, s2
	v_lshl_add_u32 v228, v228, 2, s2
	v_lshl_add_u32 v213, v213, 2, s2
	v_lshl_add_u32 v229, v229, 2, s2
	v_lshl_add_u32 v214, v214, 2, s2
	v_lshl_add_u32 v230, v230, 2, s2
	v_lshl_add_u32 v215, v215, 2, s2
	v_lshl_add_u32 v231, v231, 2, s2
	v_lshl_add_u32 v216, v216, 2, s2
	v_lshl_add_u32 v232, v232, 2, s2
	v_lshl_add_u32 v217, v217, 2, s2
	v_lshl_add_u32 v233, v233, 2, s2
	v_lshl_add_u32 v218, v218, 2, s2
	v_lshl_add_u32 v234, v234, 2, s2
	v_lshl_add_u32 v219, v219, 2, s2
	v_lshl_add_u32 v235, v235, 2, s2
	v_lshl_add_u32 v220, v220, 2, s2
	v_lshl_add_u32 v176, v176, 2, s2
	v_lshl_add_u32 v221, v221, 2, s2
	v_lshl_add_u32 v177, v177, 2, s2
	v_lshl_add_u32 v222, v222, 2, s2
	v_lshl_add_u32 v178, v178, 2, s2
	v_lshl_add_u32 v223, v223, 2, s2
	v_lshl_add_u32 v179, v179, 2, s2
	v_lshl_add_u32 v224, v224, 2, s2
	v_lshl_add_u32 v242, v242, 2, s2
	v_lshl_add_u32 v225, v225, 2, s2
	v_lshl_add_u32 v243, v243, 2, s2
	v_lshl_add_u32 v226, v226, 2, s2
	v_lshl_add_u32 v244, v244, 2, s2
	v_lshl_add_u32 v227, v227, 2, s2
	v_lshl_add_u32 v245, v245, 2, s2
	ds_read_b32 v212, v212
	ds_read_b32 v228, v228 offset:128
	ds_read_b32 v213, v213
	ds_read_b32 v229, v229 offset:128
	ds_read_b32 v214, v214
	ds_read_b32 v230, v230 offset:128
	ds_read_b32 v215, v215
	ds_read_b32 v231, v231 offset:128
	ds_read_b32 v216, v216
	ds_read_b32 v232, v232 offset:128
	ds_read_b32 v217, v217
	ds_read_b32 v233, v233 offset:128
	ds_read_b32 v218, v218
	ds_read_b32 v234, v234 offset:128
	ds_read_b32 v219, v219
	ds_read_b32 v235, v235 offset:128
	ds_read_b32 v220, v220
	ds_read_b32 v176, v176 offset:128
	ds_read_b32 v221, v221
	ds_read_b32 v177, v177 offset:128
	ds_read_b32 v222, v222
	ds_read_b32 v178, v178 offset:128
	ds_read_b32 v223, v223
	ds_read_b32 v179, v179 offset:128
	ds_read_b32 v224, v224
	ds_read_b32 v242, v242 offset:128
	ds_read_b32 v225, v225
	ds_read_b32 v243, v243 offset:128
	ds_read_b32 v226, v226
	ds_read_b32 v244, v244 offset:128
	ds_read_b32 v227, v227
	ds_read_b32 v245, v245 offset:128
	s_waitcnt lgkmcnt(0)
	v_add_f32_e32 v80, v80, v212
	v_add_f32_e32 v196, v196, v228
	v_add_f32_e32 v81, v81, v213
	v_add_f32_e32 v197, v197, v229
	v_add_f32_e32 v82, v82, v214
	v_add_f32_e32 v198, v198, v230
	v_add_f32_e32 v83, v83, v215
	v_add_f32_e32 v199, v199, v231
	v_add_f32_e32 v84, v84, v216
	v_add_f32_e32 v200, v200, v232
	v_add_f32_e32 v85, v85, v217
	v_add_f32_e32 v201, v201, v233
	v_add_f32_e32 v86, v86, v218
	v_add_f32_e32 v202, v202, v234
	v_add_f32_e32 v87, v87, v219
	v_add_f32_e32 v203, v203, v235
	v_add_f32_e32 v88, v88, v220
	v_add_f32_e32 v204, v204, v176
	v_add_f32_e32 v89, v89, v221
	v_add_f32_e32 v205, v205, v177
	v_add_f32_e32 v90, v90, v222
	v_add_f32_e32 v206, v206, v178
	v_add_f32_e32 v91, v91, v223
	v_add_f32_e32 v207, v207, v179
	v_add_f32_e32 v92, v92, v224
	v_add_f32_e32 v208, v208, v242
	v_add_f32_e32 v93, v93, v225
	v_add_f32_e32 v209, v209, v243
	v_add_f32_e32 v94, v94, v226
	v_add_f32_e32 v210, v210, v244
	v_add_f32_e32 v95, v95, v227
	v_add_f32_e32 v211, v211, v245

; DI f32x16 mfma32(bf16x8 a, bf16x8 b, f32x16 c) { return __builtin_amdgcn_mfma_f32_32x32x16_bf16(a, b, c, 0, 0, 0); }
; DI void attn_mla_unit(const Params& p, int b, int h, int qb, char* smem, bool pre, int nh, bool has_next) {
;     ...
;       f32x16 s0, s1;
; #pragma unroll
;       for (int i = 0; i < 16; ++i) { s0[i] = -m; s1[i] = -m; }
;       {
;         bf16x8 kf[12];
; #pragma unroll
;         for (int s = 0; s < 6; ++s) {
;           kf[2 * s] = *(const bf16x8*)(ks + (sub * 64 + r32) * KR + (s * 16 + hh * 8) * 2);
;           kf[2 * s + 1] = *(const bf16x8*)(ks + (sub * 64 + 32 + r32) * KR + (s * 16 + hh * 8) * 2);
;         }
;         __builtin_amdgcn_sched_barrier(0); __builtin_amdgcn_s_setprio(1);
; #pragma unroll
;         for (int s = 0; s < 6; ++s) { s0 = mfma32(kf[2 * s], qf[s], s0); s1 = mfma32(kf[2 * s + 1], qf[s], s1); }
;       __builtin_amdgcn_s_setprio(0);
; }
;       float alpha; bf16x8 pf[4];
;       const bool resc = softmax_tile(s0, s1, m, l, alpha, pf, lane, (kt == 0) && (sub == 0), (sub == 0) && ((kt & 3) == 0));
.LBB0_1482:
	s_add_i32 s19, s18, -1
	s_bitcmp1_b32 s19, 0
	s_cselect_b32 s16, 0xc800, 0
	s_add_i32 s20, s16, 0
	v_add_u32_e32 v44, s20, v149
	v_add_u32_e32 v67, v44, v144
	ds_read_b128 v[68:71], v67
	ds_read_b128 v[72:75], v67 offset:32
	ds_read_b128 v[76:79], v67 offset:6656
	ds_read_b128 v[132:135], v67 offset:6688
	ds_read_b128 v[154:157], v67 offset:64
	ds_read_b128 v[158:161], v67 offset:96
	ds_read_b128 v[162:165], v67 offset:6720
	ds_read_b128 v[166:169], v67 offset:6752
	ds_read_b128 v[170:173], v67 offset:128
	ds_read_b128 v[174:177], v67 offset:160
	ds_read_b128 v[178:181], v67 offset:6784
	ds_read_b128 v[196:199], v67 offset:6816
	v_xor_b32_e32 v32, 0x80000000, v150
	v_mov_b32_e32 v33, v32
	v_mov_b64_e32 v[34:35], v[32:33]
	v_mov_b64_e32 v[36:37], v[32:33]
	v_mov_b64_e32 v[38:39], v[32:33]
	v_mov_b64_e32 v[40:41], v[32:33]
	v_mov_b64_e32 v[42:43], v[32:33]
	v_mov_b64_e32 v[44:45], v[32:33]
	v_mov_b64_e32 v[46:47], v[32:33]
	s_and_b32 s16, s19, 3
	s_setprio 1
	s_waitcnt lgkmcnt(8)
	v_mfma_f32_32x32x16_bf16 v[48:63], v[68:71], v[100:103], v[32:47]
	v_mfma_f32_32x32x16_bf16 v[32:47], v[76:79], v[100:103], v[32:47]
	v_mfma_f32_32x32x16_bf16 v[48:63], v[72:75], v[96:99], v[48:63]
	v_mfma_f32_32x32x16_bf16 v[32:47], v[132:135], v[96:99], v[32:47]
	s_waitcnt lgkmcnt(4)
	v_mfma_f32_32x32x16_bf16 v[48:63], v[154:157], v[92:95], v[48:63]
	v_mfma_f32_32x32x16_bf16 v[32:47], v[162:165], v[92:95], v[32:47]
	v_mfma_f32_32x32x16_bf16 v[48:63], v[158:161], v[88:91], v[48:63]
	v_mfma_f32_32x32x16_bf16 v[32:47], v[166:169], v[88:91], v[32:47]
	s_waitcnt lgkmcnt(0)
	v_mfma_f32_32x32x16_bf16 v[48:63], v[170:173], v[84:87], v[48:63]
	v_mfma_f32_32x32x16_bf16 v[32:47], v[178:181], v[84:87], v[32:47]
	v_mfma_f32_32x32x16_bf16 v[48:63], v[174:177], v[80:83], v[48:63]
	v_mfma_f32_32x32x16_bf16 v[32:47], v[196:199], v[80:83], v[32:47]
	s_setprio 0
	s_nop 9
	v_exp_f32_e32 v48, v48
	v_exp_f32_e32 v49, v49
	v_exp_f32_e32 v50, v50
	v_exp_f32_e32 v51, v51
	v_add_f32_e32 v66, 0, v48
	v_exp_f32_e32 v52, v52
	v_add_f32_e32 v66, v49, v66
	v_exp_f32_e32 v53, v53
	v_add_f32_e32 v66, v50, v66
	v_exp_f32_e32 v54, v54
	v_add_f32_e32 v66, v51, v66
	v_exp_f32_e32 v55, v55
	v_add_f32_e32 v66, v52, v66
	v_exp_f32_e32 v56, v56
	v_add_f32_e32 v66, v53, v66
	v_exp_f32_e32 v57, v57
	v_add_f32_e32 v66, v54, v66
	v_exp_f32_e32 v58, v58
	v_add_f32_e32 v66, v55, v66
	v_exp_f32_e32 v59, v59
	v_add_f32_e32 v66, v56, v66
	v_exp_f32_e32 v60, v60
	v_add_f32_e32 v66, v57, v66
	v_exp_f32_e32 v61, v61
	v_add_f32_e32 v66, v58, v66
	v_exp_f32_e32 v62, v62
	v_add_f32_e32 v66, v59, v66
	v_exp_f32_e32 v63, v63
	v_add_f32_e32 v66, v60, v66
	v_exp_f32_e32 v68, v32
	v_add_f32_e32 v66, v61, v66
	v_exp_f32_e32 v33, v33
	v_add_f32_e32 v66, v62, v66
	v_exp_f32_e32 v34, v34
	v_add_f32_e32 v66, v63, v66
	v_exp_f32_e32 v35, v35
	v_add_f32_e32 v32, v68, v66
	v_exp_f32_e32 v36, v36
	v_add_f32_e32 v32, v33, v32
	v_exp_f32_e32 v37, v37
	v_add_f32_e32 v32, v34, v32
	v_exp_f32_e32 v38, v38
	v_add_f32_e32 v32, v35, v32
	v_exp_f32_e32 v39, v39
	v_add_f32_e32 v32, v36, v32
	v_exp_f32_e32 v40, v40
	v_add_f32_e32 v32, v37, v32
	v_exp_f32_e32 v41, v41
	v_add_f32_e32 v32, v38, v32
	v_exp_f32_e32 v42, v42
	v_add_f32_e32 v32, v39, v32
	v_exp_f32_e32 v43, v43
	v_add_f32_e32 v32, v40, v32
	v_exp_f32_e32 v44, v44
	v_add_f32_e32 v32, v41, v32
	v_exp_f32_e32 v45, v45
	v_add_f32_e32 v32, v42, v32
	v_exp_f32_e32 v46, v46
	v_add_f32_e32 v32, v43, v32
	v_exp_f32_e32 v47, v47
	v_add_f32_e32 v32, v44, v32
	v_add_f32_e32 v32, v45, v32
	v_add_f32_e32 v32, v46, v32
	v_add_f32_e32 v32, v47, v32
	s_cmp_lg_u32 s16, 0
	v_add_f32_e32 v66, v153, v32
	s_cbranch_scc0 .LBB0_1484
	s_mov_b64 s[16:17], 0
	v_mov_b32_e32 v32, 1.0
	s_branch .LBB0_1487

; DI f32x16 mfma32(bf16x8 a, bf16x8 b, f32x16 c) { return __builtin_amdgcn_mfma_f32_32x32x16_bf16(a, b, c, 0, 0, 0); }
; DI void attn_mla_unit(const Params& p, int b, int h, int qb, char* smem, bool pre, int nh, bool has_next) {
;     ...
;       f32x16 s0, s1;
; #pragma unroll
;       for (int i = 0; i < 16; ++i) { s0[i] = -m; s1[i] = -m; }
;       {
;         bf16x8 kf[12];
; #pragma unroll
;         for (int s = 0; s < 6; ++s) {
;           kf[2 * s] = *(const bf16x8*)(ks + (sub * 64 + r32) * KR + (s * 16 + hh * 8) * 2);
;           kf[2 * s + 1] = *(const bf16x8*)(ks + (sub * 64 + 32 + r32) * KR + (s * 16 + hh * 8) * 2);
;         }
;         __builtin_amdgcn_sched_barrier(0); __builtin_amdgcn_s_setprio(1);
; #pragma unroll
;         for (int s = 0; s < 6; ++s) { s0 = mfma32(kf[2 * s], qf[s], s0); s1 = mfma32(kf[2 * s + 1], qf[s], s1); }
;       __builtin_amdgcn_s_setprio(0);
; }
;       float alpha; bf16x8 pf[4];
;       const bool resc = softmax_tile(s0, s1, m, l, alpha, pf, lane, (kt == 0) && (sub == 0), (sub == 0) && ((kt & 3) == 0));
;       {
;         bf16x8 vf[8];
; #pragma unroll
;         for (int s = 0; s < 4; ++s) { vf[2 * s] = ld_vfrag_tr(vs, vbase, VR, sub * 64 + 16 * s, 0); vf[2 * s + 1] = ld_vfrag_tr(vs, vbase, VR, sub * 64 + 16 * s, 32); }
;         __builtin_amdgcn_sched_barrier(0); __builtin_amdgcn_s_setprio(1);
; #pragma unroll
;         for (int s = 0; s < 4; ++s) { O0 = mfma32(vf[2 * s], pf[s], O0); O1 = mfma32(vf[2 * s + 1], pf[s], O1); }
;       __builtin_amdgcn_s_setprio(0);
; }
;       if (resc) { scale16(O0, alpha); scale16(O1, alpha); }
;     }
;     if (kt + 1 < 32) put_stage(smem + ((kt + 1) & 1) * STG);
;     else if (has_next) put_stage(smem);
;     __syncthreads();
;     if (kt + 2 < 32) get_stage(kt + 2);
;     else if (kt == 30 && has_next) { gk += (nh - h) * 64; gv += (nh - h) * 64; get_stage(0); }
.LBB0_1489:
	ds_read_b128 v[70:73], v67 offset:13312
	ds_read_b128 v[74:77], v67 offset:13344
	ds_read_b128 v[132:135], v67 offset:19968
	ds_read_b128 v[154:157], v67 offset:20000
	ds_read_b128 v[158:161], v67 offset:13376
	ds_read_b128 v[162:165], v67 offset:13408
	ds_read_b128 v[166:169], v67 offset:20032
	ds_read_b128 v[170:173], v67 offset:20064
	ds_read_b128 v[174:177], v67 offset:13440
	ds_read_b128 v[178:181], v67 offset:13472
	ds_read_b128 v[196:199], v67 offset:20096
	ds_read_b128 v[200:203], v67 offset:20128
	v_xor_b32_e32 v32, 0x80000000, v150
	v_mov_b32_e32 v33, v32
	v_mov_b64_e32 v[34:35], v[32:33]
	v_mov_b64_e32 v[36:37], v[32:33]
	v_mov_b64_e32 v[38:39], v[32:33]
	v_mov_b64_e32 v[40:41], v[32:33]
	v_mov_b64_e32 v[42:43], v[32:33]
	v_mov_b64_e32 v[44:45], v[32:33]
	v_mov_b64_e32 v[46:47], v[32:33]
	s_setprio 1
	s_waitcnt lgkmcnt(8)
	v_mfma_f32_32x32x16_bf16 v[48:63], v[70:73], v[100:103], v[32:47]
	v_mfma_f32_32x32x16_bf16 v[32:47], v[132:135], v[100:103], v[32:47]
	v_mfma_f32_32x32x16_bf16 v[48:63], v[74:77], v[96:99], v[48:63]
	v_mfma_f32_32x32x16_bf16 v[32:47], v[154:157], v[96:99], v[32:47]
	s_waitcnt lgkmcnt(4)
	v_mfma_f32_32x32x16_bf16 v[48:63], v[158:161], v[92:95], v[48:63]
	v_mfma_f32_32x32x16_bf16 v[32:47], v[166:169], v[92:95], v[32:47]
	v_mfma_f32_32x32x16_bf16 v[48:63], v[162:165], v[88:91], v[48:63]
	v_mfma_f32_32x32x16_bf16 v[32:47], v[170:173], v[88:91], v[32:47]
	s_waitcnt lgkmcnt(0)
	v_mfma_f32_32x32x16_bf16 v[48:63], v[174:177], v[84:87], v[48:63]
	v_mfma_f32_32x32x16_bf16 v[32:47], v[196:199], v[84:87], v[32:47]
	v_mfma_f32_32x32x16_bf16 v[48:63], v[178:181], v[80:83], v[48:63]
	v_mfma_f32_32x32x16_bf16 v[32:47], v[200:203], v[80:83], v[32:47]
	s_setprio 0
	ds_read_b64_tr_b16 v[132:133], v68 offset:38912
	ds_read_b64_tr_b16 v[134:135], v68 offset:40448
	ds_read_b64_tr_b16 v[156:157], v68 offset:40512
	ds_read_b64_tr_b16 v[154:155], v68 offset:38976
	ds_read_b64_tr_b16 v[158:159], v68 offset:41984
	ds_read_b64_tr_b16 v[160:161], v68 offset:43520
	ds_read_b64_tr_b16 v[164:165], v68 offset:43584
	ds_read_b64_tr_b16 v[162:163], v68 offset:42048
	ds_read_b64_tr_b16 v[166:167], v68 offset:45056
	ds_read_b64_tr_b16 v[168:169], v68 offset:46592
	ds_read_b64_tr_b16 v[172:173], v68 offset:46656
	ds_read_b64_tr_b16 v[170:171], v68 offset:45120
	ds_read_b64_tr_b16 v[174:175], v68 offset:48128
	ds_read_b64_tr_b16 v[176:177], v68 offset:49664
	ds_read_b64_tr_b16 v[180:181], v68 offset:49728
	ds_read_b64_tr_b16 v[178:179], v68 offset:48192
	v_exp_f32_e32 v40, v40
	v_exp_f32_e32 v41, v41
	v_exp_f32_e32 v42, v42
	v_exp_f32_e32 v43, v43
	v_exp_f32_e32 v44, v44
	v_exp_f32_e32 v45, v45
	v_exp_f32_e32 v46, v46
	v_exp_f32_e32 v47, v47
	v_exp_f32_e32 v48, v48
	v_exp_f32_e32 v49, v49
	v_exp_f32_e32 v50, v50
	v_exp_f32_e32 v51, v51
	v_exp_f32_e32 v52, v52
	v_exp_f32_e32 v53, v53
	v_exp_f32_e32 v54, v54
	v_exp_f32_e32 v55, v55
	v_exp_f32_e32 v56, v56
	v_exp_f32_e32 v57, v57
	v_exp_f32_e32 v58, v58
	v_exp_f32_e32 v59, v59
	v_exp_f32_e32 v60, v60
	v_exp_f32_e32 v61, v61
	v_exp_f32_e32 v62, v62
	v_exp_f32_e32 v63, v63
	v_exp_f32_e32 v67, v32
	v_exp_f32_e32 v69, v33
	v_exp_f32_e32 v70, v34
	v_exp_f32_e32 v71, v35
	v_exp_f32_e32 v36, v36
	v_exp_f32_e32 v37, v37
	v_exp_f32_e32 v38, v38
	v_exp_f32_e32 v39, v39
	v_cvt_pk_bf16_f32 v32, v40, v41
	v_cvt_pk_bf16_f32 v33, v42, v43
	v_cvt_pk_bf16_f32 v34, v44, v45
	v_cvt_pk_bf16_f32 v35, v46, v47
	v_cvt_pk_bf16_f32 v72, v67, v69
	v_cvt_pk_bf16_f32 v73, v70, v71
	v_cvt_pk_bf16_f32 v74, v36, v37
	v_cvt_pk_bf16_f32 v75, v38, v39
	v_cvt_pk_bf16_f32 v76, v56, v57
	v_cvt_pk_bf16_f32 v77, v58, v59
	v_cvt_pk_bf16_f32 v78, v60, v61
	v_cvt_pk_bf16_f32 v79, v62, v63
	v_cvt_pk_bf16_f32 v196, v48, v49
	v_cvt_pk_bf16_f32 v197, v50, v51
	v_cvt_pk_bf16_f32 v198, v52, v53
	v_cvt_pk_bf16_f32 v199, v54, v55
	s_setprio 1
	s_waitcnt lgkmcnt(8)
	v_mfma_f32_32x32x16_bf16 v[16:31], v[132:135], v[196:199], v[16:31]
	v_mfma_f32_32x32x16_bf16 v[0:15], v[154:157], v[196:199], v[0:15]
	v_mfma_f32_32x32x16_bf16 v[16:31], v[158:161], v[76:79], v[16:31]
	v_mfma_f32_32x32x16_bf16 v[0:15], v[162:165], v[76:79], v[0:15]
	s_waitcnt lgkmcnt(0)
	v_mfma_f32_32x32x16_bf16 v[16:31], v[166:169], v[72:75], v[16:31]
	v_mfma_f32_32x32x16_bf16 v[0:15], v[170:173], v[72:75], v[0:15]
	v_mfma_f32_32x32x16_bf16 v[16:31], v[174:177], v[32:35], v[16:31]
	v_mfma_f32_32x32x16_bf16 v[0:15], v[178:181], v[32:35], v[0:15]
	s_setprio 0
	s_bitcmp1_b32 s18, 0
	s_cselect_b32 s16, 0xc800, 0
	s_add_i32 s16, s16, 0
	v_add3_u32 v32, s16, v142, v138
	v_add3_u32 v33, s16, v139, v138
	s_waitcnt vmcnt(4)
	ds_write_b128 v32, v[104:107]
	s_waitcnt vmcnt(2)
	ds_write_b128 v33, v[108:111] offset:26624
	s_waitcnt vmcnt(2)
	ds_write_b128 v32, v[112:115] offset:13312
	s_waitcnt vmcnt(1)
	ds_write_b128 v33, v[116:119] offset:38912
	v_add3_u32 v32, s16, v143, v146
	s_cmp_gt_u32 s19, 29
	s_mov_b64 s[16:17], -1
	s_waitcnt vmcnt(0)
	ds_write_b128 v32, v[120:123] offset:128
	s_waitcnt lgkmcnt(0)
	s_barrier
	s_cbranch_scc0 .LBB0_1493
	s_cmp_lg_u32 s12, 0x410000
	s_cselect_b64 s[16:17], -1, 0
	s_xor_b64 s[20:21], s[10:11], -1
	s_or_b64 s[16:17], s[20:21], s[16:17]
	s_and_b64 vcc, exec, s[16:17]
	v_mov_b64_e32 v[32:33], v[128:129]
	v_mov_b64_e32 v[34:35], v[130:131]
	s_cbranch_vccnz .LBB0_1492
	v_lshl_add_u64 v[32:33], v[128:129], 0, s[14:15]
	v_add_co_u32_e32 v72, vcc, 0x10000, v32
	v_lshl_add_u64 v[34:35], v[130:131], 0, s[14:15]
	s_nop 0
	v_addc_co_u32_e32 v73, vcc, 0, v33, vcc
	global_load_dwordx4 v[104:107], v[32:33], off
	global_load_dwordx4 v[112:115], v[72:73], off
	v_add_co_u32_e32 v72, vcc, 0x10000, v34
	s_nop 1
	v_addc_co_u32_e32 v73, vcc, 0, v35, vcc
	global_load_dwordx4 v[108:111], v[34:35], off
	global_load_dwordx4 v[116:119], v[72:73], off
	global_load_dwordx4 v[120:123], v[126:127], off

; DI f32x16 mfma32(bf16x8 a, bf16x8 b, f32x16 c) { return __builtin_amdgcn_mfma_f32_32x32x16_bf16(a, b, c, 0, 0, 0); }
; DI void attn_na_unit(const Params& p, int li, int b, int r, int hp, char* smem) {
;     ...
;     f32x16 s0, s1;
; #pragma unroll
;     for (int i = 0; i < 16; ++i) { s0[i] = -m; s1[i] = -m; }
;     {
;       bf16x8 kf[8];
; #pragma unroll
;       for (int s = 0; s < 4; ++s) {
;         kf[2 * s] = *(const bf16x8*)(ks + r32 * KR + (hs * 64 + s * 16 + hh * 8) * 2);
;         kf[2 * s + 1] = *(const bf16x8*)(ks + (32 + r32) * KR + (hs * 64 + s * 16 + hh * 8) * 2);
;       }
;       __builtin_amdgcn_sched_barrier(0); __builtin_amdgcn_s_setprio(1);
; #pragma unroll
;       for (int s = 0; s < 4; ++s) { s0 = mfma32(kf[2 * s], qf[s], s0); s1 = mfma32(kf[2 * s + 1], qf[s], s1); }
;     __builtin_amdgcn_s_setprio(0);
; }
;     const int drow = rs + kt - r + 7;
;     const float* trow = tab + hs * 465 + drow * 31;
; #pragma unroll
;     for (int i = 0; i < 16; ++i) {
;       const int kc0 = (i & 3) + 8 * (i >> 2) + 4 * hh;
;       const int kc1 = kc0 + 32;
;       const bool v0 = (unsigned)(kc0 - cs) < 16u;
;       const bool v1 = (unsigned)(kc1 - cs) < 16u;
;       const int d0 = v0 ? (kc0 - wq + 15) : 0;
;       const int d1 = v1 ? (kc1 - wq + 15) : 0;
;       const float b0 = trow[d0], b1 = trow[d1];
;       s0[i] = v0 ? s0[i] + b0 : -1e30f;
.LBB0_1541:
	ds_read_b128 v[150:153], v123
	ds_read_b128 v[154:157], v123 offset:32
	ds_read_b128 v[158:161], v123 offset:8704
	ds_read_b128 v[162:165], v123 offset:8736
	ds_read_b128 v[166:169], v123 offset:64
	ds_read_b128 v[170:173], v123 offset:96
	ds_read_b128 v[174:177], v123 offset:8768
	ds_read_b128 v[178:181], v123 offset:8800
	v_xor_b32_e32 v32, 0x80000000, v128
	v_mov_b32_e32 v33, v32
	v_mov_b64_e32 v[34:35], v[32:33]
	v_mov_b64_e32 v[36:37], v[32:33]
	v_mov_b64_e32 v[38:39], v[32:33]
	v_mov_b64_e32 v[40:41], v[32:33]
	v_mov_b64_e32 v[42:43], v[32:33]
	v_mov_b64_e32 v[44:45], v[32:33]
	v_mov_b64_e32 v[46:47], v[32:33]
	s_setprio 1
	s_waitcnt lgkmcnt(7)
	v_mfma_f32_32x32x16_bf16 v[48:63], v[150:153], v[64:67], v[32:47]
	s_waitcnt lgkmcnt(5)
	v_mfma_f32_32x32x16_bf16 v[32:47], v[158:161], v[64:67], v[32:47]
	v_mfma_f32_32x32x16_bf16 v[48:63], v[154:157], v[68:71], v[48:63]
	s_waitcnt lgkmcnt(4)
	v_mfma_f32_32x32x16_bf16 v[32:47], v[162:165], v[68:71], v[32:47]
	s_waitcnt lgkmcnt(3)
	v_mfma_f32_32x32x16_bf16 v[48:63], v[166:169], v[72:75], v[48:63]
	s_waitcnt lgkmcnt(1)
	v_mfma_f32_32x32x16_bf16 v[32:47], v[174:177], v[72:75], v[32:47]
	v_mfma_f32_32x32x16_bf16 v[48:63], v[170:173], v[76:79], v[48:63]
	s_waitcnt lgkmcnt(0)
	v_mfma_f32_32x32x16_bf16 v[32:47], v[178:181], v[76:79], v[32:47]
	s_setprio 0
	v_add_u32_e32 v149, s9, v129
	ds_read_b32 v150, v149 offset:868
	v_mov_b32_e32 v149, 0xf149f2ca
	v_add_u32_e32 v154, s9, v130
	v_mov_b32_e32 v151, 0xf149f2ca
	s_and_saveexec_b64 s[6:7], s[76:77]
	s_cbranch_execz .LBB0_1543
	ds_read_b32 v151, v154 offset:868
	s_waitcnt lgkmcnt(0)
	v_add_f32_e32 v151, v48, v151

; #define PG8_STAGE(bufoff, gbase, voff) do { _Pragma("unroll") for (int _i = 0; _i < 2; ++_i) \
;     __builtin_amdgcn_global_load_lds((const unsigned*)((const char*)(gbase) + (voff)[_i]), (LAS unsigned*)(lds + (bufoff) + ldsw + _i * 8192), 16, 0, 0); } while (0)
; #define PG8_LDA(dst, b, h) do { _Pragma("unroll") for (int m = 0; m < 4; ++m) _Pragma("unroll") for (int k = 0; k < 2; ++k) dst[m][k] = *(const LAS bf16x8*)(lds + PG8_SA(b, h) + aoff + m * 2048 + k * 1024); } while (0)
; #define PG8_LDB(dst, b, h) do { _Pragma("unroll") for (int n = 0; n < 2; ++n) _Pragma("unroll") for (int k = 0; k < 2; ++k) dst[n][k] = *(const LAS bf16x8*)(lds + PG8_SB(b, h) + boff + n * 2048 + k * 1024); } while (0)
; #define PG8_MMA(ai, bj, At, Bt) do { __builtin_amdgcn_s_setprio(1); _Pragma("unroll") for (int m = 0; m < 4; ++m) _Pragma("unroll") for (int n = 0; n < 2; ++n) _Pragma("unroll") for (int k = 0; k < 2; ++k) \
;     acc[ai][bj][m][n] = __builtin_amdgcn_mfma_f32_16x16x32_bf16(Bt[n][k], At[m][k], acc[ai][bj][m][n], 0, 0, 0); __builtin_amdgcn_s_setprio(0); } while (0)
; #define PG8_WAIT_V(n) asm volatile("s_waitcnt vmcnt(" #n ")" ::: "memory")
; #define PG8_WAIT_L(n) asm volatile("s_waitcnt lgkmcnt(" #n ")" ::: "memory")
; #define PG8_BAR __builtin_amdgcn_s_barrier()
; #define PG8_SCHED __builtin_amdgcn_sched_barrier(0)
; template <class Epi, class Sched>
; DI void gemm_phase(LAS unsigned char* lds, const Gemm g, const Sched& S, const Epi& E) {
;     ...
;     for (int t = 0; t < nt; t += 2) {
;       const bool last = (t == nt - 2);
;       const char* a1 = cA + (size_t)(t + 1) * kstep;
;       const char* a2 = last ? nA : cA + (size_t)(t + 2) * kstep; const char* b2 = last ? nB : cB + (size_t)(t + 2) * kstep;
;       const char* a3 = a2 + kstep; const char* b3 = b2 + kstep;
;       PG8_LDB(B0, 0, 0); PG8_SCHED; PG8_LDA(At, 0, 0); PG8_STAGE(PG8_SA(1, 1), a1 + hstep, voffA);
;       PG8_WAIT_L(8); PG8_BAR; PG8_WAIT_L(0); PG8_MMA(0, 0, At, B0); PG8_BAR; PG8_SCHED;
;       PG8_LDB(B1, 0, 1); PG8_STAGE(PG8_SB(0, 0), b2, voffB);
;       PG8_BAR; PG8_WAIT_L(0); PG8_MMA(0, 1, At, B1); PG8_BAR;
;       PG8_LDA(At, 0, 1); PG8_STAGE(PG8_SA(0, 0), a2, voffA);
;       PG8_BAR; PG8_WAIT_L(0); PG8_MMA(1, 0, At, B0); PG8_BAR; PG8_SCHED;
;       PG8_STAGE(PG8_SB(0, 1), b2 + hstep, voffB);
;       PG8_WAIT_V(6); PG8_BAR; PG8_MMA(1, 1, At, B1); PG8_BAR;
.LBB0_1829:
	s_add_u32 s16, s14, 0xfffc0080
	s_addc_u32 s17, s15, -1
	s_add_i32 s51, 0, 0x10000
	v_add_u32_e32 v140, s51, v142
	ds_read_b128 v[146:149], v140
	ds_read_b128 v[150:153], v140 offset:1024
	ds_read_b128 v[154:157], v140 offset:2048
	ds_read_b128 v[158:161], v140 offset:3072
	s_cmp_eq_u32 s50, 12
	s_cselect_b32 s19, s7, s17
	s_cselect_b32 s18, s46, s16
	s_cselect_b32 s17, s5, s49
	s_cselect_b32 s16, s47, s48
	v_lshl_add_u64 v[140:141], s[14:15], 0, v[136:137]
	s_add_i32 m0, s29, 0xc000
	ds_read_b128 v[162:165], v143
	ds_read_b128 v[166:169], v143 offset:1024
	ds_read_b128 v[170:173], v143 offset:2048
	ds_read_b128 v[174:177], v143 offset:3072
	ds_read_b128 v[178:181], v143 offset:4096
	ds_read_b128 v[196:199], v143 offset:5120
	ds_read_b128 v[200:203], v143 offset:6144
	ds_read_b128 v[204:207], v143 offset:7168
	global_load_lds_dwordx4 v[140:141], off
	v_lshl_add_u64 v[140:141], s[14:15], 0, v[138:139]
	s_add_i32 m0, s29, 0xe000
	s_nop 0
	global_load_lds_dwordx4 v[140:141], off
	s_waitcnt lgkmcnt(8)
	s_barrier
	s_waitcnt lgkmcnt(0)
	s_setprio 1
	s_waitcnt lgkmcnt(0)
	v_mfma_f32_16x16x32_bf16 v[124:127], v[146:149], v[162:165], v[124:127]
	v_mfma_f32_16x16x32_bf16 v[120:123], v[154:157], v[162:165], v[120:123]
	v_mfma_f32_16x16x32_bf16 v[112:115], v[146:149], v[170:173], v[112:115]
	v_mfma_f32_16x16x32_bf16 v[104:107], v[154:157], v[170:173], v[104:107]
	v_mfma_f32_16x16x32_bf16 v[92:95], v[146:149], v[178:181], v[92:95]
	v_mfma_f32_16x16x32_bf16 v[88:91], v[154:157], v[178:181], v[88:91]
	v_mfma_f32_16x16x32_bf16 v[80:83], v[146:149], v[200:203], v[80:83]
	v_mfma_f32_16x16x32_bf16 v[72:75], v[154:157], v[200:203], v[72:75]
	v_mfma_f32_16x16x32_bf16 v[124:127], v[150:153], v[166:169], v[124:127]
	v_mfma_f32_16x16x32_bf16 v[120:123], v[158:161], v[166:169], v[120:123]
	v_mfma_f32_16x16x32_bf16 v[112:115], v[150:153], v[174:177], v[112:115]
	v_mfma_f32_16x16x32_bf16 v[104:107], v[158:161], v[174:177], v[104:107]
	v_mfma_f32_16x16x32_bf16 v[92:95], v[150:153], v[196:199], v[92:95]
	v_mfma_f32_16x16x32_bf16 v[88:91], v[158:161], v[196:199], v[88:91]
	v_mfma_f32_16x16x32_bf16 v[80:83], v[150:153], v[204:207], v[80:83]
	v_mfma_f32_16x16x32_bf16 v[72:75], v[158:161], v[204:207], v[72:75]
	s_setprio 0
	s_barrier
	s_add_i32 s54, 0, 0x14000
	v_add_u32_e32 v140, s54, v142
	s_add_i32 s51, s51, s20
	ds_read_b128 v[208:211], v140
	ds_read_b128 v[212:215], v140 offset:1024
	ds_read_b128 v[216:219], v140 offset:2048
	ds_read_b128 v[220:223], v140 offset:3072
	v_lshl_add_u64 v[140:141], s[16:17], 0, v[132:133]
	s_mov_b32 m0, s51
	v_lshl_add_u64 v[224:225], s[16:17], 0, v[128:129]
	global_load_lds_dwordx4 v[140:141], off
	s_add_i32 m0, s51, 0x2000
	s_nop 0
	global_load_lds_dwordx4 v[224:225], off
	s_barrier
	s_waitcnt lgkmcnt(0)
	s_setprio 1
	s_waitcnt lgkmcnt(0)
	v_mfma_f32_16x16x32_bf16 v[116:119], v[208:211], v[162:165], v[116:119]
	v_mfma_f32_16x16x32_bf16 v[108:111], v[216:219], v[162:165], v[108:111]
	v_mfma_f32_16x16x32_bf16 v[100:103], v[208:211], v[170:173], v[100:103]
	v_mfma_f32_16x16x32_bf16 v[96:99], v[216:219], v[170:173], v[96:99]
	v_mfma_f32_16x16x32_bf16 v[84:87], v[208:211], v[178:181], v[84:87]
	v_mfma_f32_16x16x32_bf16 v[76:79], v[216:219], v[178:181], v[76:79]
	v_mfma_f32_16x16x32_bf16 v[68:71], v[208:211], v[200:203], v[68:71]
	v_mfma_f32_16x16x32_bf16 v[64:67], v[216:219], v[200:203], v[64:67]
	v_mfma_f32_16x16x32_bf16 v[116:119], v[212:215], v[166:169], v[116:119]
	v_mfma_f32_16x16x32_bf16 v[108:111], v[220:223], v[166:169], v[108:111]
	v_mfma_f32_16x16x32_bf16 v[100:103], v[212:215], v[174:177], v[100:103]
	v_mfma_f32_16x16x32_bf16 v[96:99], v[220:223], v[174:177], v[96:99]
	v_mfma_f32_16x16x32_bf16 v[84:87], v[212:215], v[196:199], v[84:87]
	v_mfma_f32_16x16x32_bf16 v[76:79], v[220:223], v[196:199], v[76:79]
	v_mfma_f32_16x16x32_bf16 v[68:71], v[212:215], v[204:207], v[68:71]
	v_mfma_f32_16x16x32_bf16 v[64:67], v[220:223], v[204:207], v[64:67]
	s_setprio 0
	s_mov_b32 m0, s29
	v_lshl_add_u64 v[226:227], s[18:19], 0, v[134:135]
	s_barrier
	ds_read_b128 v[162:165], v143 offset:16384
	ds_read_b128 v[166:169], v143 offset:17408
	ds_read_b128 v[170:173], v143 offset:18432
	ds_read_b128 v[174:177], v143 offset:19456
	ds_read_b128 v[178:181], v143 offset:20480
	ds_read_b128 v[196:199], v143 offset:21504
	ds_read_b128 v[200:203], v143 offset:22528
	ds_read_b128 v[204:207], v143 offset:23552
	global_load_lds_dwordx4 v[226:227], off
	v_lshl_add_u64 v[228:229], s[18:19], 0, v[130:131]
	s_mov_b32 m0, s34
	s_nop 0
	global_load_lds_dwordx4 v[228:229], off
	s_barrier
	s_waitcnt lgkmcnt(0)
	s_setprio 1
	s_waitcnt lgkmcnt(0)
	v_mfma_f32_16x16x32_bf16 v[60:63], v[146:149], v[162:165], v[60:63]
	v_mfma_f32_16x16x32_bf16 v[56:59], v[154:157], v[162:165], v[56:59]
	v_mfma_f32_16x16x32_bf16 v[48:51], v[146:149], v[170:173], v[48:51]
	v_mfma_f32_16x16x32_bf16 v[40:43], v[154:157], v[170:173], v[40:43]
	v_mfma_f32_16x16x32_bf16 v[28:31], v[146:149], v[178:181], v[28:31]
	v_mfma_f32_16x16x32_bf16 v[24:27], v[154:157], v[178:181], v[24:27]
	v_mfma_f32_16x16x32_bf16 v[16:19], v[146:149], v[200:203], v[16:19]
	v_mfma_f32_16x16x32_bf16 v[8:11], v[154:157], v[200:203], v[8:11]
	v_mfma_f32_16x16x32_bf16 v[60:63], v[150:153], v[166:169], v[60:63]
	v_mfma_f32_16x16x32_bf16 v[56:59], v[158:161], v[166:169], v[56:59]
	v_mfma_f32_16x16x32_bf16 v[48:51], v[150:153], v[174:177], v[48:51]
	v_mfma_f32_16x16x32_bf16 v[40:43], v[158:161], v[174:177], v[40:43]
	v_mfma_f32_16x16x32_bf16 v[28:31], v[150:153], v[196:199], v[28:31]
	v_mfma_f32_16x16x32_bf16 v[24:27], v[158:161], v[196:199], v[24:27]
	v_mfma_f32_16x16x32_bf16 v[16:19], v[150:153], v[204:207], v[16:19]
	v_mfma_f32_16x16x32_bf16 v[8:11], v[158:161], v[204:207], v[8:11]
	s_setprio 0
	s_barrier
; #define PG8_STAGE(bufoff, gbase, voff) do { _Pragma("unroll") for (int _i = 0; _i < 2; ++_i) \
;     __builtin_amdgcn_global_load_lds((const unsigned*)((const char*)(gbase) + (voff)[_i]), (LAS unsigned*)(lds + (bufoff) + ldsw + _i * 8192), 16, 0, 0); } while (0)
; #define PG8_LDA(dst, b, h) do { _Pragma("unroll") for (int m = 0; m < 4; ++m) _Pragma("unroll") for (int k = 0; k < 2; ++k) dst[m][k] = *(const LAS bf16x8*)(lds + PG8_SA(b, h) + aoff + m * 2048 + k * 1024); } while (0)
; #define PG8_LDB(dst, b, h) do { _Pragma("unroll") for (int n = 0; n < 2; ++n) _Pragma("unroll") for (int k = 0; k < 2; ++k) dst[n][k] = *(const LAS bf16x8*)(lds + PG8_SB(b, h) + boff + n * 2048 + k * 1024); } while (0)
; #define PG8_MMA(ai, bj, At, Bt) do { __builtin_amdgcn_s_setprio(1); _Pragma("unroll") for (int m = 0; m < 4; ++m) _Pragma("unroll") for (int n = 0; n < 2; ++n) _Pragma("unroll") for (int k = 0; k < 2; ++k) \
;     acc[ai][bj][m][n] = __builtin_amdgcn_mfma_f32_16x16x32_bf16(Bt[n][k], At[m][k], acc[ai][bj][m][n], 0, 0, 0); __builtin_amdgcn_s_setprio(0); } while (0)
; #define PG8_WAIT_V(n) asm volatile("s_waitcnt vmcnt(" #n ")" ::: "memory")
; #define PG8_WAIT_L(n) asm volatile("s_waitcnt lgkmcnt(" #n ")" ::: "memory")
; #define PG8_BAR __builtin_amdgcn_s_barrier()
; #define PG8_SCHED __builtin_amdgcn_sched_barrier(0)
; template <class Epi, class Sched>
; DI void gemm_phase(LAS unsigned char* lds, const Gemm g, const Sched& S, const Epi& E) {
;     ...
;       PG8_WAIT_V(6); PG8_BAR; PG8_MMA(1, 1, At, B1); PG8_BAR;
;       PG8_LDB(B0, 1, 0); PG8_SCHED; PG8_LDA(At, 1, 0); PG8_STAGE(PG8_SA(0, 1), a2 + hstep, voffA);
;       PG8_WAIT_L(8); PG8_BAR; PG8_WAIT_L(0); PG8_MMA(0, 0, At, B0); PG8_BAR; PG8_SCHED;
;       PG8_LDB(B1, 1, 1); PG8_STAGE(PG8_SB(1, 0), b3, voffB);
;       PG8_BAR; PG8_WAIT_L(0); PG8_MMA(0, 1, At, B1); PG8_BAR;
;       PG8_LDA(At, 1, 1); PG8_STAGE(PG8_SA(1, 0), a3, voffA);
;       PG8_BAR; PG8_WAIT_L(0); PG8_MMA(1, 0, At, B0); PG8_BAR; PG8_SCHED;
	s_add_u32 s52, s16, 0x40000
	s_addc_u32 s53, s17, 0
	s_add_i32 s51, s54, s20
	v_lshl_add_u64 v[146:147], s[52:53], 0, v[132:133]
	s_mov_b32 m0, s51
	s_nop 0
	global_load_lds_dwordx4 v[146:147], off
	v_lshl_add_u64 v[146:147], s[52:53], 0, v[128:129]
	s_add_i32 m0, s51, 0x2000
	s_nop 0
	global_load_lds_dwordx4 v[146:147], off
	s_waitcnt vmcnt(6)
	s_barrier
	s_setprio 1
	v_mfma_f32_16x16x32_bf16 v[52:55], v[208:211], v[162:165], v[52:55]
	v_mfma_f32_16x16x32_bf16 v[44:47], v[216:219], v[162:165], v[44:47]
	v_mfma_f32_16x16x32_bf16 v[36:39], v[208:211], v[170:173], v[36:39]
	v_mfma_f32_16x16x32_bf16 v[32:35], v[216:219], v[170:173], v[32:35]
	v_mfma_f32_16x16x32_bf16 v[20:23], v[208:211], v[178:181], v[20:23]
	v_mfma_f32_16x16x32_bf16 v[12:15], v[216:219], v[178:181], v[12:15]
	v_mfma_f32_16x16x32_bf16 v[4:7], v[208:211], v[200:203], v[4:7]
	v_mfma_f32_16x16x32_bf16 v[0:3], v[216:219], v[200:203], v[0:3]
	v_mfma_f32_16x16x32_bf16 v[52:55], v[212:215], v[166:169], v[52:55]
	v_mfma_f32_16x16x32_bf16 v[44:47], v[220:223], v[166:169], v[44:47]
	v_mfma_f32_16x16x32_bf16 v[36:39], v[212:215], v[174:177], v[36:39]
	v_mfma_f32_16x16x32_bf16 v[32:35], v[220:223], v[174:177], v[32:35]
	v_mfma_f32_16x16x32_bf16 v[20:23], v[212:215], v[196:199], v[20:23]
	v_mfma_f32_16x16x32_bf16 v[12:15], v[220:223], v[196:199], v[12:15]
	v_mfma_f32_16x16x32_bf16 v[4:7], v[212:215], v[204:207], v[4:7]
	v_mfma_f32_16x16x32_bf16 v[0:3], v[220:223], v[204:207], v[0:3]
	s_setprio 0
	s_add_i32 s51, 0, 0x18000
	v_add_u32_e32 v144, s51, v142
	s_barrier
	ds_read_b128 v[146:149], v144
	ds_read_b128 v[150:153], v144 offset:1024
	ds_read_b128 v[154:157], v144 offset:2048
	ds_read_b128 v[158:161], v144 offset:3072
	s_add_u32 s18, s18, 0x40000
	s_addc_u32 s19, s19, 0
	s_mov_b32 m0, s35
	v_lshl_add_u64 v[208:209], s[18:19], 0, v[134:135]
	ds_read_b128 v[162:165], v143 offset:32768
	ds_read_b128 v[166:169], v143 offset:33792
	ds_read_b128 v[170:173], v143 offset:34816
	ds_read_b128 v[174:177], v143 offset:35840
	ds_read_b128 v[178:181], v143 offset:36864
	ds_read_b128 v[196:199], v143 offset:37888
	ds_read_b128 v[200:203], v143 offset:38912
	ds_read_b128 v[204:207], v143 offset:39936
	global_load_lds_dwordx4 v[208:209], off
	v_lshl_add_u64 v[208:209], s[18:19], 0, v[130:131]
	s_mov_b32 m0, s38
	s_nop 0
	global_load_lds_dwordx4 v[208:209], off
	s_waitcnt lgkmcnt(8)
	s_barrier
	s_waitcnt lgkmcnt(0)
	s_setprio 1
	s_waitcnt lgkmcnt(0)
	v_mfma_f32_16x16x32_bf16 v[124:127], v[146:149], v[162:165], v[124:127]
	v_mfma_f32_16x16x32_bf16 v[120:123], v[154:157], v[162:165], v[120:123]
	v_mfma_f32_16x16x32_bf16 v[112:115], v[146:149], v[170:173], v[112:115]
	v_mfma_f32_16x16x32_bf16 v[104:107], v[154:157], v[170:173], v[104:107]
	v_mfma_f32_16x16x32_bf16 v[92:95], v[146:149], v[178:181], v[92:95]
	v_mfma_f32_16x16x32_bf16 v[88:91], v[154:157], v[178:181], v[88:91]
	v_mfma_f32_16x16x32_bf16 v[80:83], v[146:149], v[200:203], v[80:83]
	v_mfma_f32_16x16x32_bf16 v[72:75], v[154:157], v[200:203], v[72:75]
	v_mfma_f32_16x16x32_bf16 v[124:127], v[150:153], v[166:169], v[124:127]
	v_mfma_f32_16x16x32_bf16 v[120:123], v[158:161], v[166:169], v[120:123]
	v_mfma_f32_16x16x32_bf16 v[112:115], v[150:153], v[174:177], v[112:115]
	v_mfma_f32_16x16x32_bf16 v[104:107], v[158:161], v[174:177], v[104:107]
	v_mfma_f32_16x16x32_bf16 v[92:95], v[150:153], v[196:199], v[92:95]
	v_mfma_f32_16x16x32_bf16 v[88:91], v[158:161], v[196:199], v[88:91]
	v_mfma_f32_16x16x32_bf16 v[80:83], v[150:153], v[204:207], v[80:83]
	v_mfma_f32_16x16x32_bf16 v[72:75], v[158:161], v[204:207], v[72:75]
	s_setprio 0
	s_barrier
	s_add_i32 s18, 0, 0x1c000
	s_add_i32 s19, s51, s20
	v_add_u32_e32 v144, s18, v142
	v_lshl_add_u64 v[140:141], v[140:141], 0, s[0:1]
	s_mov_b32 m0, s19
	ds_read_b128 v[208:211], v144
	ds_read_b128 v[212:215], v144 offset:1024
	ds_read_b128 v[216:219], v144 offset:2048
	ds_read_b128 v[220:223], v144 offset:3072
	global_load_lds_dwordx4 v[140:141], off
	v_lshl_add_u64 v[140:141], v[224:225], 0, s[0:1]
	s_add_i32 m0, s19, 0x2000
	s_nop 0
	global_load_lds_dwordx4 v[140:141], off
	s_barrier
	s_waitcnt lgkmcnt(0)
	s_setprio 1
	s_waitcnt lgkmcnt(0)
	v_mfma_f32_16x16x32_bf16 v[116:119], v[208:211], v[162:165], v[116:119]
	v_mfma_f32_16x16x32_bf16 v[108:111], v[216:219], v[162:165], v[108:111]
	v_mfma_f32_16x16x32_bf16 v[100:103], v[208:211], v[170:173], v[100:103]
	v_mfma_f32_16x16x32_bf16 v[96:99], v[216:219], v[170:173], v[96:99]
	v_mfma_f32_16x16x32_bf16 v[84:87], v[208:211], v[178:181], v[84:87]
	v_mfma_f32_16x16x32_bf16 v[76:79], v[216:219], v[178:181], v[76:79]
	v_mfma_f32_16x16x32_bf16 v[68:71], v[208:211], v[200:203], v[68:71]
	v_mfma_f32_16x16x32_bf16 v[64:67], v[216:219], v[200:203], v[64:67]
	v_mfma_f32_16x16x32_bf16 v[116:119], v[212:215], v[166:169], v[116:119]
	v_mfma_f32_16x16x32_bf16 v[108:111], v[220:223], v[166:169], v[108:111]
	v_mfma_f32_16x16x32_bf16 v[100:103], v[212:215], v[174:177], v[100:103]
	v_mfma_f32_16x16x32_bf16 v[96:99], v[220:223], v[174:177], v[96:99]
	v_mfma_f32_16x16x32_bf16 v[84:87], v[212:215], v[196:199], v[84:87]
	v_mfma_f32_16x16x32_bf16 v[76:79], v[220:223], v[196:199], v[76:79]
	v_mfma_f32_16x16x32_bf16 v[68:71], v[212:215], v[204:207], v[68:71]
	v_mfma_f32_16x16x32_bf16 v[64:67], v[220:223], v[204:207], v[64:67]
	s_setprio 0
	s_mov_b32 m0, s40
	v_lshl_add_u64 v[140:141], v[226:227], 0, s[0:1]
	s_barrier
	ds_read_b128 v[162:165], v143 offset:49152
	ds_read_b128 v[166:169], v143 offset:50176
	ds_read_b128 v[170:173], v143 offset:51200
	ds_read_b128 v[174:177], v143 offset:52224
	ds_read_b128 v[178:181], v143 offset:53248
	ds_read_b128 v[196:199], v143 offset:54272
	ds_read_b128 v[200:203], v143 offset:55296
	ds_read_b128 v[204:207], v143 offset:56320
	global_load_lds_dwordx4 v[140:141], off
	v_lshl_add_u64 v[140:141], v[228:229], 0, s[0:1]
	s_mov_b32 m0, s41
	s_nop 0
	global_load_lds_dwordx4 v[140:141], off
	s_barrier
; #define PG8_MMA(ai, bj, At, Bt) do { __builtin_amdgcn_s_setprio(1); _Pragma("unroll") for (int m = 0; m < 4; ++m) _Pragma("unroll") for (int n = 0; n < 2; ++n) _Pragma("unroll") for (int k = 0; k < 2; ++k) \
;     acc[ai][bj][m][n] = __builtin_amdgcn_mfma_f32_16x16x32_bf16(Bt[n][k], At[m][k], acc[ai][bj][m][n], 0, 0, 0); __builtin_amdgcn_s_setprio(0); } while (0)
; #define PG8_WAIT_V(n) asm volatile("s_waitcnt vmcnt(" #n ")" ::: "memory")
; #define PG8_BAR __builtin_amdgcn_s_barrier()
; template <class Epi, class Sched>
; DI void gemm_phase(LAS unsigned char* lds, const Gemm g, const Sched& S, const Epi& E) {
;     ...
;       PG8_WAIT_V(6); PG8_BAR; PG8_MMA(1, 1, At, B1); PG8_BAR;
;     }
;     E(acc, cur, wr, wc, fr, fq);
;   DI void operator()(const f32x4 (&acc)[2][2][4][2], const pg8::Unit& u, int wr, int wc, int fr_, int fq_) const {
;     ...
;               if (n == 0) {
;                 const f32x4 v1 = acc[ai][bj][m][1];
;                 u32x4 o4;
;                 { const float t0 = fmaxf(v[0], 0.f) * rinv, t1 = fmaxf(v[1], 0.f) * rinv, t2 = fmaxf(v[2], 0.f) * rinv, t3 = fmaxf(v[3], 0.f) * rinv;
;                   o4.x = pack2(t0 * t0, t1 * t1); o4.y = pack2(t2 * t2, t3 * t3); }
;                 { const float t0 = fmaxf(v1[0], 0.f) * rinv, t1 = fmaxf(v1[1], 0.f) * rinv, t2 = fmaxf(v1[2], 0.f) * rinv, t3 = fmaxf(v1[3], 0.f) * rinv;
;                   o4.z = pack2(t0 * t0, t1 * t1); o4.w = pack2(t2 * t2, t3 * t3); }
;                 *(u32x4*)((u16*)big + (size_t)token * 4096 + u.pn * 256 + bj * 128 + wc * 32 + 8 * fq) = o4;
	s_waitcnt lgkmcnt(0)
	s_setprio 1
	s_waitcnt lgkmcnt(0)
	v_mfma_f32_16x16x32_bf16 v[60:63], v[146:149], v[162:165], v[60:63]
	v_mfma_f32_16x16x32_bf16 v[56:59], v[154:157], v[162:165], v[56:59]
	v_mfma_f32_16x16x32_bf16 v[48:51], v[146:149], v[170:173], v[48:51]
	v_mfma_f32_16x16x32_bf16 v[40:43], v[154:157], v[170:173], v[40:43]
	v_mfma_f32_16x16x32_bf16 v[28:31], v[146:149], v[178:181], v[28:31]
	v_mfma_f32_16x16x32_bf16 v[24:27], v[154:157], v[178:181], v[24:27]
	v_mfma_f32_16x16x32_bf16 v[16:19], v[146:149], v[200:203], v[16:19]
	v_mfma_f32_16x16x32_bf16 v[8:11], v[154:157], v[200:203], v[8:11]
	v_mfma_f32_16x16x32_bf16 v[60:63], v[150:153], v[166:169], v[60:63]
	v_mfma_f32_16x16x32_bf16 v[56:59], v[158:161], v[166:169], v[56:59]
	v_mfma_f32_16x16x32_bf16 v[48:51], v[150:153], v[174:177], v[48:51]
	v_mfma_f32_16x16x32_bf16 v[40:43], v[158:161], v[174:177], v[40:43]
	v_mfma_f32_16x16x32_bf16 v[28:31], v[150:153], v[196:199], v[28:31]
	v_mfma_f32_16x16x32_bf16 v[24:27], v[158:161], v[196:199], v[24:27]
	v_mfma_f32_16x16x32_bf16 v[16:19], v[150:153], v[204:207], v[16:19]
	v_mfma_f32_16x16x32_bf16 v[8:11], v[158:161], v[204:207], v[8:11]
	s_setprio 0
	s_barrier
	s_add_u32 s16, s16, 0x40080
	s_addc_u32 s17, s17, 0
	s_add_i32 s18, s18, s20
	v_lshl_add_u64 v[140:141], s[16:17], 0, v[132:133]
	s_mov_b32 m0, s18
	s_nop 0
	global_load_lds_dwordx4 v[140:141], off
	v_lshl_add_u64 v[140:141], s[16:17], 0, v[128:129]
	s_add_i32 m0, s18, 0x2000
	s_nop 0
	global_load_lds_dwordx4 v[140:141], off
	s_waitcnt vmcnt(6)
	s_barrier
	s_setprio 1
	v_mfma_f32_16x16x32_bf16 v[52:55], v[208:211], v[162:165], v[52:55]
	v_mfma_f32_16x16x32_bf16 v[44:47], v[216:219], v[162:165], v[44:47]
	v_mfma_f32_16x16x32_bf16 v[36:39], v[208:211], v[170:173], v[36:39]
	v_mfma_f32_16x16x32_bf16 v[32:35], v[216:219], v[170:173], v[32:35]
	v_mfma_f32_16x16x32_bf16 v[20:23], v[208:211], v[178:181], v[20:23]
	v_mfma_f32_16x16x32_bf16 v[12:15], v[216:219], v[178:181], v[12:15]
	v_mfma_f32_16x16x32_bf16 v[4:7], v[208:211], v[200:203], v[4:7]
	v_mfma_f32_16x16x32_bf16 v[0:3], v[216:219], v[200:203], v[0:3]
	v_mfma_f32_16x16x32_bf16 v[52:55], v[212:215], v[166:169], v[52:55]
	v_mfma_f32_16x16x32_bf16 v[44:47], v[220:223], v[166:169], v[44:47]
	v_mfma_f32_16x16x32_bf16 v[36:39], v[212:215], v[174:177], v[36:39]
	v_mfma_f32_16x16x32_bf16 v[32:35], v[220:223], v[174:177], v[32:35]
	v_mfma_f32_16x16x32_bf16 v[20:23], v[212:215], v[196:199], v[20:23]
	v_mfma_f32_16x16x32_bf16 v[12:15], v[220:223], v[196:199], v[12:15]
	v_mfma_f32_16x16x32_bf16 v[4:7], v[212:215], v[204:207], v[4:7]
	v_mfma_f32_16x16x32_bf16 v[0:3], v[220:223], v[204:207], v[0:3]
	s_setprio 0
	s_add_i32 s50, s50, 2
	s_add_u32 s14, s14, 0x100
	s_addc_u32 s15, s15, 0
	s_add_u32 s48, s48, 0x100
	s_addc_u32 s49, s49, 0
	s_cmp_gt_u32 s50, 13
	s_barrier
	s_cbranch_scc0 .LBB0_1829
	v_mov_b32_e32 v144, v182
	s_lshl_b32 s5, s43, 10
	s_add_i32 s5, s5, 0
	v_and_or_b32 v141, v144, 15, s39
	v_lshl_add_u32 v140, s44, 8, v141
	v_lshl_add_u32 v141, v141, 2, s5
	v_add_u32_e32 v146, 0x20000, v141
	ds_read2_b32 v[148:149], v146 offset1:16
	v_max_f32_e32 v124, 0, v124
	v_max_f32_e32 v125, 0, v125
	v_max_f32_e32 v126, 0, v126
	v_max_f32_e32 v127, 0, v127
	v_max_f32_e32 v120, 0, v120
	v_max_f32_e32 v121, 0, v121
	s_waitcnt lgkmcnt(0)
	v_pk_mul_f32 v[124:125], v[124:125], v[148:149] op_sel_hi:[1,0]
	v_pk_mul_f32 v[126:127], v[126:127], v[148:149] op_sel_hi:[1,0]
	v_pk_mul_f32 v[120:121], v[120:121], v[148:149] op_sel_hi:[1,0]
	v_pk_mul_f32 v[124:125], v[124:125], v[124:125]
	v_pk_mul_f32 v[126:127], v[126:127], v[126:127]
	v_max_f32_e32 v122, 0, v122
	v_max_f32_e32 v123, 0, v123
	v_pk_mul_f32 v[120:121], v[120:121], v[120:121]
	v_max_f32_e32 v116, 0, v116
	v_max_f32_e32 v117, 0, v117
	v_max_f32_e32 v118, 0, v118
	v_max_f32_e32 v119, 0, v119
	v_max_f32_e32 v108, 0, v108
	v_max_f32_e32 v109, 0, v109
	s_lshl_b32 s14, s45, 8
	v_ashrrev_i32_e32 v141, 31, v140
	v_cvt_pk_bf16_f32 v124, v124, v125
	v_cvt_pk_bf16_f32 v125, v126, v127
	v_cvt_pk_bf16_f32 v126, v120, v121
	v_pk_mul_f32 v[120:121], v[122:123], v[148:149] op_sel_hi:[1,0]
	v_pk_mul_f32 v[116:117], v[116:117], v[148:149] op_sel_hi:[1,0]
	v_pk_mul_f32 v[118:119], v[118:119], v[148:149] op_sel_hi:[1,0]
	v_pk_mul_f32 v[108:109], v[108:109], v[148:149] op_sel_hi:[1,0]
	s_ashr_i32 s15, s14, 31
	v_lshlrev_b64 v[150:151], 13, v[140:141]
	v_pk_mul_f32 v[120:121], v[120:121], v[120:121]
	v_pk_mul_f32 v[116:117], v[116:117], v[116:117]
	v_pk_mul_f32 v[118:119], v[118:119], v[118:119]
	v_max_f32_e32 v110, 0, v110
	v_max_f32_e32 v111, 0, v111
	v_pk_mul_f32 v[108:109], v[108:109], v[108:109]
	v_cvt_pk_bf16_f32 v127, v120, v121
	v_lshl_add_u64 v[120:121], s[2:3], 0, v[150:151]
	s_lshl_b64 s[14:15], s[14:15], 1
	v_cvt_pk_bf16_f32 v116, v116, v117
	v_cvt_pk_bf16_f32 v117, v118, v119
	v_cvt_pk_bf16_f32 v118, v108, v109
	v_pk_mul_f32 v[108:109], v[110:111], v[148:149] op_sel_hi:[1,0]
	v_lshl_add_u64 v[120:121], v[120:121], 0, s[14:15]
	v_pk_mul_f32 v[108:109], v[108:109], v[108:109]
	v_lshl_add_u64 v[120:121], v[120:121], 0, s[24:25]
	v_and_b32_e32 v144, 48, v144
	v_cvt_pk_bf16_f32 v119, v108, v109
	v_add_u32_e32 v108, 16, v140
	v_lshl_add_u64 v[120:121], v[120:121], 0, v[144:145]
	v_ashrrev_i32_e32 v109, 31, v108
	global_store_dwordx4 v[120:121], v[116:119], off offset:256
	v_max_f32_e32 v100, 0, v100
	v_max_f32_e32 v101, 0, v101
	v_lshlrev_b64 v[116:117], 13, v[108:109]
	v_max_f32_e32 v108, v112, v112
	v_mov_b32_e32 v112, v149
	v_max_f32_e32 v102, 0, v102
	v_max_f32_e32 v103, 0, v103
	v_max_f32_e32 v96, 0, v96
	v_max_f32_e32 v97, 0, v97
	v_pk_mul_f32 v[100:101], v[100:101], v[112:113] op_sel_hi:[1,0]
	v_pk_mul_f32 v[102:103], v[102:103], v[112:113] op_sel_hi:[1,0]
	v_pk_mul_f32 v[96:97], v[96:97], v[112:113] op_sel_hi:[1,0]
	v_pk_mul_f32 v[100:101], v[100:101], v[100:101]
	v_pk_mul_f32 v[102:103], v[102:103], v[102:103]
	v_max_f32_e32 v98, 0, v98
	v_max_f32_e32 v99, 0, v99
	v_pk_mul_f32 v[96:97], v[96:97], v[96:97]
	v_cvt_pk_bf16_f32 v100, v100, v101
	v_cvt_pk_bf16_f32 v101, v102, v103
	v_cvt_pk_bf16_f32 v102, v96, v97
	v_pk_mul_f32 v[96:97], v[98:99], v[112:113] op_sel_hi:[1,0]
	ds_read2_b32 v[98:99], v146 offset0:32 offset1:48
	v_max_f32_e32 v92, 0, v92
	v_max_f32_e32 v93, 0, v93
	v_max_f32_e32 v94, 0, v94
	v_max_f32_e32 v95, 0, v95
	v_max_f32_e32 v88, 0, v88
	v_max_f32_e32 v89, 0, v89
	v_pk_mul_f32 v[96:97], v[96:97], v[96:97]
	s_waitcnt lgkmcnt(0)
;   DI void operator()(const f32x4 (&acc)[2][2][4][2], const pg8::Unit& u, int wr, int wc, int fr_, int fq_) const {
;     ...
;             } else {
;               if (n == 0) {
;                 const f32x4 v1 = acc[ai][bj][m][1];
;                 u32x4 o4;
;                 { const float t0 = fmaxf(v[0], 0.f) * rinv, t1 = fmaxf(v[1], 0.f) * rinv, t2 = fmaxf(v[2], 0.f) * rinv, t3 = fmaxf(v[3], 0.f) * rinv;
;                   o4.x = pack2(t0 * t0, t1 * t1); o4.y = pack2(t2 * t2, t3 * t3); }
;                 { const float t0 = fmaxf(v1[0], 0.f) * rinv, t1 = fmaxf(v1[1], 0.f) * rinv, t2 = fmaxf(v1[2], 0.f) * rinv, t3 = fmaxf(v1[3], 0.f) * rinv;
;                   o4.z = pack2(t0 * t0, t1 * t1); o4.w = pack2(t2 * t2, t3 * t3); }
;                 *(u32x4*)((u16*)big + (size_t)token * 4096 + u.pn * 256 + bj * 128 + wc * 32 + 8 * fq) = o4;
;               }
	v_pk_mul_f32 v[92:93], v[92:93], v[98:99] op_sel_hi:[1,0]
	v_pk_mul_f32 v[94:95], v[94:95], v[98:99] op_sel_hi:[1,0]
	v_pk_mul_f32 v[88:89], v[88:89], v[98:99] op_sel_hi:[1,0]
	v_cvt_pk_bf16_f32 v103, v96, v97
	v_add_u32_e32 v96, 32, v140
	v_pk_mul_f32 v[92:93], v[92:93], v[92:93]
	v_pk_mul_f32 v[94:95], v[94:95], v[94:95]
	v_max_f32_e32 v90, 0, v90
	v_max_f32_e32 v91, 0, v91
	v_pk_mul_f32 v[88:89], v[88:89], v[88:89]
	v_max_f32_e32 v84, 0, v84
	v_max_f32_e32 v85, 0, v85
	v_max_f32_e32 v86, 0, v86
	v_max_f32_e32 v87, 0, v87
	v_max_f32_e32 v76, 0, v76
	v_max_f32_e32 v77, 0, v77
	v_ashrrev_i32_e32 v97, 31, v96
	v_cvt_pk_bf16_f32 v92, v92, v93
	v_cvt_pk_bf16_f32 v93, v94, v95
	v_cvt_pk_bf16_f32 v94, v88, v89
	v_pk_mul_f32 v[88:89], v[90:91], v[98:99] op_sel_hi:[1,0]
	v_pk_mul_f32 v[84:85], v[84:85], v[98:99] op_sel_hi:[1,0]
	v_pk_mul_f32 v[86:87], v[86:87], v[98:99] op_sel_hi:[1,0]
	v_pk_mul_f32 v[76:77], v[76:77], v[98:99] op_sel_hi:[1,0]
	v_lshlrev_b64 v[96:97], 13, v[96:97]
	v_pk_mul_f32 v[88:89], v[88:89], v[88:89]
	v_pk_mul_f32 v[84:85], v[84:85], v[84:85]
	v_pk_mul_f32 v[86:87], v[86:87], v[86:87]
	v_max_f32_e32 v78, 0, v78
	v_max_f32_e32 v79, 0, v79
	v_pk_mul_f32 v[76:77], v[76:77], v[76:77]
	v_cvt_pk_bf16_f32 v95, v88, v89
	v_lshl_add_u64 v[88:89], s[2:3], 0, v[96:97]
	v_cvt_pk_bf16_f32 v84, v84, v85
	v_cvt_pk_bf16_f32 v85, v86, v87
	v_cvt_pk_bf16_f32 v86, v76, v77
	v_pk_mul_f32 v[76:77], v[78:79], v[98:99] op_sel_hi:[1,0]
	v_lshl_add_u64 v[88:89], v[88:89], 0, s[14:15]
	v_pk_mul_f32 v[76:77], v[76:77], v[76:77]
	v_lshl_add_u64 v[88:89], v[88:89], 0, s[24:25]
	v_cvt_pk_bf16_f32 v87, v76, v77
	v_add_u32_e32 v76, 48, v140
	v_lshl_add_u64 v[88:89], v[88:89], 0, v[144:145]
	v_ashrrev_i32_e32 v77, 31, v76
	global_store_dwordx4 v[88:89], v[84:87], off offset:256
	v_max_f32_e32 v68, 0, v68
	v_max_f32_e32 v69, 0, v69
	v_lshlrev_b64 v[84:85], 13, v[76:77]
	v_max_f32_e32 v76, v80, v80
	v_mov_b32_e32 v80, v99
	v_max_f32_e32 v70, 0, v70
	v_max_f32_e32 v71, 0, v71
	v_max_f32_e32 v64, 0, v64
	v_max_f32_e32 v65, 0, v65
	v_pk_mul_f32 v[68:69], v[68:69], v[80:81] op_sel_hi:[1,0]
	v_pk_mul_f32 v[70:71], v[70:71], v[80:81] op_sel_hi:[1,0]
	v_pk_mul_f32 v[64:65], v[64:65], v[80:81] op_sel_hi:[1,0]
	v_pk_mul_f32 v[68:69], v[68:69], v[68:69]
	v_pk_mul_f32 v[70:71], v[70:71], v[70:71]
	v_max_f32_e32 v66, 0, v66
	v_max_f32_e32 v67, 0, v67
	v_pk_mul_f32 v[64:65], v[64:65], v[64:65]
	v_cvt_pk_bf16_f32 v68, v68, v69
	v_cvt_pk_bf16_f32 v69, v70, v71
	v_cvt_pk_bf16_f32 v70, v64, v65
	v_pk_mul_f32 v[64:65], v[66:67], v[80:81] op_sel_hi:[1,0]
	ds_read2_b32 v[66:67], v146 offset0:128 offset1:144
	v_max_f32_e32 v60, 0, v60
	v_max_f32_e32 v61, 0, v61
	v_max_f32_e32 v62, 0, v62
	v_max_f32_e32 v63, 0, v63
	v_max_f32_e32 v56, 0, v56
	v_max_f32_e32 v57, 0, v57
	v_pk_mul_f32 v[64:65], v[64:65], v[64:65]
	s_waitcnt lgkmcnt(0)
	v_pk_mul_f32 v[60:61], v[60:61], v[66:67] op_sel_hi:[1,0]
	v_pk_mul_f32 v[62:63], v[62:63], v[66:67] op_sel_hi:[1,0]
	v_pk_mul_f32 v[56:57], v[56:57], v[66:67] op_sel_hi:[1,0]
	v_cvt_pk_bf16_f32 v71, v64, v65
	v_add_u32_e32 v64, 0x80, v140
	v_pk_mul_f32 v[60:61], v[60:61], v[60:61]
	v_pk_mul_f32 v[62:63], v[62:63], v[62:63]
	v_max_f32_e32 v58, 0, v58
	v_max_f32_e32 v59, 0, v59
	v_pk_mul_f32 v[56:57], v[56:57], v[56:57]
	v_max_f32_e32 v52, 0, v52
	v_max_f32_e32 v53, 0, v53
	v_max_f32_e32 v54, 0, v54
	v_max_f32_e32 v55, 0, v55
	v_max_f32_e32 v44, 0, v44
	v_max_f32_e32 v45, 0, v45
	v_ashrrev_i32_e32 v65, 31, v64
	v_cvt_pk_bf16_f32 v60, v60, v61
	v_cvt_pk_bf16_f32 v61, v62, v63
	v_cvt_pk_bf16_f32 v62, v56, v57
	v_pk_mul_f32 v[56:57], v[58:59], v[66:67] op_sel_hi:[1,0]
	v_pk_mul_f32 v[52:53], v[52:53], v[66:67] op_sel_hi:[1,0]
	v_pk_mul_f32 v[54:55], v[54:55], v[66:67] op_sel_hi:[1,0]
	v_pk_mul_f32 v[44:45], v[44:45], v[66:67] op_sel_hi:[1,0]
	v_lshlrev_b64 v[64:65], 13, v[64:65]
	v_pk_mul_f32 v[56:57], v[56:57], v[56:57]
	v_pk_mul_f32 v[52:53], v[52:53], v[52:53]
	v_pk_mul_f32 v[54:55], v[54:55], v[54:55]
	v_max_f32_e32 v46, 0, v46
	v_max_f32_e32 v47, 0, v47
	v_pk_mul_f32 v[44:45], v[44:45], v[44:45]
	v_cvt_pk_bf16_f32 v63, v56, v57
	v_lshl_add_u64 v[56:57], s[2:3], 0, v[64:65]
	v_cvt_pk_bf16_f32 v52, v52, v53
	v_cvt_pk_bf16_f32 v53, v54, v55
	v_cvt_pk_bf16_f32 v54, v44, v45
	v_pk_mul_f32 v[44:45], v[46:47], v[66:67] op_sel_hi:[1,0]
	v_lshl_add_u64 v[56:57], v[56:57], 0, s[14:15]
	v_pk_mul_f32 v[44:45], v[44:45], v[44:45]
	v_lshl_add_u64 v[56:57], v[56:57], 0, s[24:25]
	v_cvt_pk_bf16_f32 v55, v44, v45
	v_add_u32_e32 v44, 0x90, v140
	v_lshl_add_u64 v[56:57], v[56:57], 0, v[144:145]
	v_ashrrev_i32_e32 v45, 31, v44
	global_store_dwordx4 v[56:57], v[52:55], off offset:256
	v_max_f32_e32 v36, 0, v36
	v_max_f32_e32 v37, 0, v37
	v_lshlrev_b64 v[52:53], 13, v[44:45]
	v_max_f32_e32 v44, v48, v48
	v_mov_b32_e32 v48, v67
	v_max_f32_e32 v38, 0, v38
	v_max_f32_e32 v39, 0, v39
	v_max_f32_e32 v32, 0, v32
	v_max_f32_e32 v33, 0, v33
	v_pk_mul_f32 v[36:37], v[36:37], v[48:49] op_sel_hi:[1,0]
	v_pk_mul_f32 v[38:39], v[38:39], v[48:49] op_sel_hi:[1,0]
	v_pk_mul_f32 v[32:33], v[32:33], v[48:49] op_sel_hi:[1,0]
	v_pk_mul_f32 v[36:37], v[36:37], v[36:37]
	v_pk_mul_f32 v[38:39], v[38:39], v[38:39]
	v_max_f32_e32 v34, 0, v34
	v_max_f32_e32 v35, 0, v35
	v_pk_mul_f32 v[32:33], v[32:33], v[32:33]
	v_cvt_pk_bf16_f32 v36, v36, v37
	v_cvt_pk_bf16_f32 v37, v38, v39
	v_cvt_pk_bf16_f32 v38, v32, v33
	v_pk_mul_f32 v[32:33], v[34:35], v[48:49] op_sel_hi:[1,0]
	ds_read2_b32 v[34:35], v146 offset0:160 offset1:176
	v_max_f32_e32 v28, 0, v28
	v_max_f32_e32 v29, 0, v29
	v_max_f32_e32 v30, 0, v30
	v_max_f32_e32 v31, 0, v31
	v_max_f32_e32 v24, 0, v24
	v_max_f32_e32 v25, 0, v25
	v_pk_mul_f32 v[32:33], v[32:33], v[32:33]
	s_waitcnt lgkmcnt(0)
;   DI void operator()(const f32x4 (&acc)[2][2][4][2], const pg8::Unit& u, int wr, int wc, int fr_, int fq_) const {
;     ...
;             } else {
;               if (n == 0) {
;                 const f32x4 v1 = acc[ai][bj][m][1];
;                 u32x4 o4;
;                 { const float t0 = fmaxf(v[0], 0.f) * rinv, t1 = fmaxf(v[1], 0.f) * rinv, t2 = fmaxf(v[2], 0.f) * rinv, t3 = fmaxf(v[3], 0.f) * rinv;
;                   o4.x = pack2(t0 * t0, t1 * t1); o4.y = pack2(t2 * t2, t3 * t3); }
;                 { const float t0 = fmaxf(v1[0], 0.f) * rinv, t1 = fmaxf(v1[1], 0.f) * rinv, t2 = fmaxf(v1[2], 0.f) * rinv, t3 = fmaxf(v1[3], 0.f) * rinv;
;                   o4.z = pack2(t0 * t0, t1 * t1); o4.w = pack2(t2 * t2, t3 * t3); }
;                 *(u32x4*)((u16*)big + (size_t)token * 4096 + u.pn * 256 + bj * 128 + wc * 32 + 8 * fq) = o4;
;               }
	v_pk_mul_f32 v[28:29], v[28:29], v[34:35] op_sel_hi:[1,0]
	v_pk_mul_f32 v[30:31], v[30:31], v[34:35] op_sel_hi:[1,0]
	v_pk_mul_f32 v[24:25], v[24:25], v[34:35] op_sel_hi:[1,0]
	v_cvt_pk_bf16_f32 v39, v32, v33
	v_add_u32_e32 v32, 0xa0, v140
	v_pk_mul_f32 v[28:29], v[28:29], v[28:29]
	v_pk_mul_f32 v[30:31], v[30:31], v[30:31]
	v_max_f32_e32 v26, 0, v26
	v_max_f32_e32 v27, 0, v27
	v_pk_mul_f32 v[24:25], v[24:25], v[24:25]
	v_max_f32_e32 v20, 0, v20
	v_max_f32_e32 v21, 0, v21
	v_max_f32_e32 v22, 0, v22
	v_max_f32_e32 v23, 0, v23
	v_max_f32_e32 v12, 0, v12
	v_max_f32_e32 v13, 0, v13
	v_ashrrev_i32_e32 v33, 31, v32
	v_cvt_pk_bf16_f32 v28, v28, v29
	v_cvt_pk_bf16_f32 v29, v30, v31
	v_cvt_pk_bf16_f32 v30, v24, v25
	v_pk_mul_f32 v[24:25], v[26:27], v[34:35] op_sel_hi:[1,0]
	v_pk_mul_f32 v[20:21], v[20:21], v[34:35] op_sel_hi:[1,0]
	v_pk_mul_f32 v[22:23], v[22:23], v[34:35] op_sel_hi:[1,0]
	v_pk_mul_f32 v[12:13], v[12:13], v[34:35] op_sel_hi:[1,0]
	v_lshlrev_b64 v[32:33], 13, v[32:33]
	v_pk_mul_f32 v[24:25], v[24:25], v[24:25]
	v_pk_mul_f32 v[20:21], v[20:21], v[20:21]
	v_pk_mul_f32 v[22:23], v[22:23], v[22:23]
	v_max_f32_e32 v14, 0, v14
	v_max_f32_e32 v15, 0, v15
	v_pk_mul_f32 v[12:13], v[12:13], v[12:13]
	v_cvt_pk_bf16_f32 v31, v24, v25
	v_lshl_add_u64 v[24:25], s[2:3], 0, v[32:33]
	v_cvt_pk_bf16_f32 v20, v20, v21
	v_cvt_pk_bf16_f32 v21, v22, v23
	v_cvt_pk_bf16_f32 v22, v12, v13
	v_pk_mul_f32 v[12:13], v[14:15], v[34:35] op_sel_hi:[1,0]
	v_lshl_add_u64 v[24:25], v[24:25], 0, s[14:15]
	v_pk_mul_f32 v[12:13], v[12:13], v[12:13]
	v_lshl_add_u64 v[24:25], v[24:25], 0, s[24:25]
	v_cvt_pk_bf16_f32 v23, v12, v13
	v_add_u32_e32 v12, 0xb0, v140
	v_lshl_add_u64 v[24:25], v[24:25], 0, v[144:145]
	v_ashrrev_i32_e32 v13, 31, v12
	v_max_f32_e32 v109, v113, v113
	v_max_f32_e32 v110, v114, v114
	v_max_f32_e32 v111, v115, v115
	v_max_f32_e32 v77, v81, v81
	v_max_f32_e32 v78, v82, v82
	v_max_f32_e32 v79, v83, v83
	v_max_f32_e32 v45, v49, v49
	v_max_f32_e32 v46, v50, v50
	v_max_f32_e32 v47, v51, v51
	global_store_dwordx4 v[24:25], v[20:23], off offset:256
	v_max_f32_e32 v14, v18, v18
	v_max_f32_e32 v15, v19, v19
	v_lshlrev_b64 v[20:21], 13, v[12:13]
	v_max_f32_e32 v12, v16, v16
	v_max_f32_e32 v13, v17, v17
	v_max_f32_e32 v108, 0, v108
	v_max_f32_e32 v109, 0, v109
	v_max_f32_e32 v110, 0, v110
	v_max_f32_e32 v111, 0, v111
	v_max_f32_e32 v104, 0, v104
	v_max_f32_e32 v105, 0, v105
	v_max_f32_e32 v76, 0, v76
	v_max_f32_e32 v77, 0, v77
	v_max_f32_e32 v78, 0, v78
	v_max_f32_e32 v79, 0, v79
	v_max_f32_e32 v72, 0, v72
	v_max_f32_e32 v73, 0, v73
	v_max_f32_e32 v44, 0, v44
	v_max_f32_e32 v45, 0, v45
	v_max_f32_e32 v46, 0, v46
	v_max_f32_e32 v47, 0, v47
	v_max_f32_e32 v40, 0, v40
	v_max_f32_e32 v41, 0, v41
	v_max_f32_e32 v12, 0, v12
	v_max_f32_e32 v13, 0, v13
	v_max_f32_e32 v14, 0, v14
	v_max_f32_e32 v15, 0, v15
	v_mov_b32_e32 v16, v35
	v_max_f32_e32 v8, 0, v8
	v_max_f32_e32 v9, 0, v9
	v_pk_mul_f32 v[108:109], v[108:109], v[112:113] op_sel_hi:[1,0]
	v_pk_mul_f32 v[110:111], v[110:111], v[112:113] op_sel_hi:[1,0]
	v_pk_mul_f32 v[104:105], v[104:105], v[112:113] op_sel_hi:[1,0]
	v_pk_mul_f32 v[76:77], v[76:77], v[80:81] op_sel_hi:[1,0]
	v_pk_mul_f32 v[78:79], v[78:79], v[80:81] op_sel_hi:[1,0]
	v_pk_mul_f32 v[72:73], v[72:73], v[80:81] op_sel_hi:[1,0]
	v_pk_mul_f32 v[44:45], v[44:45], v[48:49] op_sel_hi:[1,0]
	v_pk_mul_f32 v[46:47], v[46:47], v[48:49] op_sel_hi:[1,0]
	v_pk_mul_f32 v[40:41], v[40:41], v[48:49] op_sel_hi:[1,0]
	v_pk_mul_f32 v[12:13], v[12:13], v[16:17] op_sel_hi:[1,0]
	v_pk_mul_f32 v[14:15], v[14:15], v[16:17] op_sel_hi:[1,0]
	v_pk_mul_f32 v[8:9], v[8:9], v[16:17] op_sel_hi:[1,0]
	v_pk_mul_f32 v[108:109], v[108:109], v[108:109]
	v_pk_mul_f32 v[110:111], v[110:111], v[110:111]
	v_max_f32_e32 v106, 0, v106
	v_max_f32_e32 v107, 0, v107
	v_pk_mul_f32 v[104:105], v[104:105], v[104:105]
; #define PG8_WAIT_V(n) asm volatile("s_waitcnt vmcnt(" #n ")" ::: "memory")
; #define PG8_BAR __builtin_amdgcn_s_barrier()
; template <class Epi, class Sched>
; DI void gemm_phase(LAS unsigned char* lds, const Gemm g, const Sched& S, const Epi& E) {
;     ...
;     E(acc, cur, wr, wc, fr, fq);
;     if (!has_next) break;
; #pragma unroll
;     for (int a = 0; a < 2; ++a)
; #pragma unroll
;       for (int b = 0; b < 2; ++b)
; #pragma unroll
;         for (int m = 0; m < 4; ++m)
; #pragma unroll
;           for (int n = 0; n < 2; ++n) acc[a][b][m][n] = (f32x4){0.f, 0.f, 0.f, 0.f};
;     cur = nxt; cA = nA; cB = nB; ++ui;
;   }
;   PG8_WAIT_V(0);
;   if (wr == 0) PG8_BAR;
;   PG8_BAR;
;   DI void operator()(const f32x4 (&acc)[2][2][4][2], const pg8::Unit& u, int wr, int wc, int fr_, int fq_) const {
;     ...
;             } else {
;               if (n == 0) {
;                 const f32x4 v1 = acc[ai][bj][m][1];
;                 u32x4 o4;
;                 { const float t0 = fmaxf(v[0], 0.f) * rinv, t1 = fmaxf(v[1], 0.f) * rinv, t2 = fmaxf(v[2], 0.f) * rinv, t3 = fmaxf(v[3], 0.f) * rinv;
;                   o4.x = pack2(t0 * t0, t1 * t1); o4.y = pack2(t2 * t2, t3 * t3); }
;                 { const float t0 = fmaxf(v1[0], 0.f) * rinv, t1 = fmaxf(v1[1], 0.f) * rinv, t2 = fmaxf(v1[2], 0.f) * rinv, t3 = fmaxf(v1[3], 0.f) * rinv;
;                   o4.z = pack2(t0 * t0, t1 * t1); o4.w = pack2(t2 * t2, t3 * t3); }
;                 *(u32x4*)((u16*)big + (size_t)token * 4096 + u.pn * 256 + bj * 128 + wc * 32 + 8 * fq) = o4;
;               }
	v_pk_mul_f32 v[76:77], v[76:77], v[76:77]
	v_pk_mul_f32 v[78:79], v[78:79], v[78:79]
	v_max_f32_e32 v74, 0, v74
	v_max_f32_e32 v75, 0, v75
	v_pk_mul_f32 v[72:73], v[72:73], v[72:73]
	v_pk_mul_f32 v[44:45], v[44:45], v[44:45]
	v_pk_mul_f32 v[46:47], v[46:47], v[46:47]
	v_max_f32_e32 v42, 0, v42
	v_max_f32_e32 v43, 0, v43
	v_pk_mul_f32 v[40:41], v[40:41], v[40:41]
	v_pk_mul_f32 v[12:13], v[12:13], v[12:13]
	v_pk_mul_f32 v[14:15], v[14:15], v[14:15]
	v_max_f32_e32 v10, 0, v10
	v_max_f32_e32 v11, 0, v11
	v_pk_mul_f32 v[8:9], v[8:9], v[8:9]
	v_cvt_pk_bf16_f32 v108, v108, v109
	v_cvt_pk_bf16_f32 v109, v110, v111
	v_cvt_pk_bf16_f32 v110, v104, v105
	v_pk_mul_f32 v[104:105], v[106:107], v[112:113] op_sel_hi:[1,0]
	v_cvt_pk_bf16_f32 v76, v76, v77
	v_cvt_pk_bf16_f32 v77, v78, v79
	v_cvt_pk_bf16_f32 v78, v72, v73
	v_pk_mul_f32 v[72:73], v[74:75], v[80:81] op_sel_hi:[1,0]
	v_cvt_pk_bf16_f32 v44, v44, v45
	v_cvt_pk_bf16_f32 v45, v46, v47
	v_cvt_pk_bf16_f32 v46, v40, v41
	v_pk_mul_f32 v[40:41], v[42:43], v[48:49] op_sel_hi:[1,0]
	v_cvt_pk_bf16_f32 v12, v12, v13
	v_cvt_pk_bf16_f32 v13, v14, v15
	v_cvt_pk_bf16_f32 v14, v8, v9
	v_pk_mul_f32 v[8:9], v[10:11], v[16:17] op_sel_hi:[1,0]
	v_max_f32_e32 v4, 0, v4
	v_max_f32_e32 v5, 0, v5
	v_max_f32_e32 v6, 0, v6
	v_max_f32_e32 v7, 0, v7
	v_max_f32_e32 v0, 0, v0
	v_max_f32_e32 v1, 0, v1
	v_pk_mul_f32 v[104:105], v[104:105], v[104:105]
	v_pk_mul_f32 v[72:73], v[72:73], v[72:73]
	v_pk_mul_f32 v[40:41], v[40:41], v[40:41]
	v_pk_mul_f32 v[8:9], v[8:9], v[8:9]
	v_pk_mul_f32 v[4:5], v[4:5], v[16:17] op_sel_hi:[1,0]
	v_pk_mul_f32 v[6:7], v[6:7], v[16:17] op_sel_hi:[1,0]
	v_pk_mul_f32 v[0:1], v[0:1], v[16:17] op_sel_hi:[1,0]
	v_cvt_pk_bf16_f32 v111, v104, v105
	v_lshl_add_u64 v[104:105], s[2:3], 0, v[116:117]
	v_cvt_pk_bf16_f32 v79, v72, v73
	v_lshl_add_u64 v[72:73], s[2:3], 0, v[84:85]
	v_cvt_pk_bf16_f32 v47, v40, v41
	v_lshl_add_u64 v[40:41], s[2:3], 0, v[52:53]
	v_cvt_pk_bf16_f32 v15, v8, v9
	v_lshl_add_u64 v[8:9], s[2:3], 0, v[20:21]
	v_pk_mul_f32 v[4:5], v[4:5], v[4:5]
	v_pk_mul_f32 v[6:7], v[6:7], v[6:7]
	v_max_f32_e32 v2, 0, v2
	v_max_f32_e32 v3, 0, v3
	v_pk_mul_f32 v[0:1], v[0:1], v[0:1]
	v_lshl_add_u64 v[104:105], v[104:105], 0, s[14:15]
	v_lshl_add_u64 v[72:73], v[72:73], 0, s[14:15]
	v_lshl_add_u64 v[40:41], v[40:41], 0, s[14:15]
	v_lshl_add_u64 v[8:9], v[8:9], 0, s[14:15]
	v_cvt_pk_bf16_f32 v4, v4, v5
	v_cvt_pk_bf16_f32 v5, v6, v7
	v_cvt_pk_bf16_f32 v6, v0, v1
	v_pk_mul_f32 v[0:1], v[2:3], v[16:17] op_sel_hi:[1,0]
	v_lshl_add_u64 v[104:105], v[104:105], 0, s[24:25]
	v_lshl_add_u64 v[72:73], v[72:73], 0, s[24:25]
	v_lshl_add_u64 v[40:41], v[40:41], 0, s[24:25]
	v_lshl_add_u64 v[8:9], v[8:9], 0, s[24:25]
	v_pk_mul_f32 v[0:1], v[0:1], v[0:1]
	v_lshl_add_u64 v[104:105], v[104:105], 0, v[144:145]
	v_lshl_add_u64 v[72:73], v[72:73], 0, v[144:145]
	v_lshl_add_u64 v[40:41], v[40:41], 0, v[144:145]
	v_lshl_add_u64 v[8:9], v[8:9], 0, v[144:145]
	v_cvt_pk_bf16_f32 v7, v0, v1
	s_and_b64 vcc, exec, s[36:37]
	s_mov_b32 s43, s42
	s_mov_b32 s45, s4
	s_mov_b32 s44, s6
	s_mov_b64 s[16:17], s[12:13]
	s_mov_b64 s[14:15], s[10:11]
	v_readlane_b32 s51, v237, 11
	global_store_dwordx4 v[120:121], v[124:127], off
	global_store_dwordx4 v[104:105], v[108:111], off
	global_store_dwordx4 v[104:105], v[100:103], off offset:256
	global_store_dwordx4 v[88:89], v[92:95], off
	global_store_dwordx4 v[72:73], v[76:79], off
	global_store_dwordx4 v[72:73], v[68:71], off offset:256
	global_store_dwordx4 v[56:57], v[60:63], off
	global_store_dwordx4 v[40:41], v[44:47], off
	global_store_dwordx4 v[40:41], v[36:39], off offset:256
	global_store_dwordx4 v[24:25], v[28:31], off
	global_store_dwordx4 v[8:9], v[12:15], off
	global_store_dwordx4 v[8:9], v[4:7], off offset:256
	s_cbranch_vccz .LBB0_1822
	s_waitcnt vmcnt(0)
	s_cmpk_gt_u32 s9, 0xff
	s_cbranch_scc1 .LBB0_1833
	s_barrier
